# attention loops: slot-rotation and loop-counter bookkeeping moved ahead of each step closing barrier; hyena A-fragment reuse across diagonals
# speedup vs baseline: 1.0064x; 1.0064x over previous
; #define WAIT_BAR(N) asm volatile("s_waitcnt vmcnt(" #N ") lgkmcnt(0)\n\ts_barrier":::"memory")
;   #define RESC() do{ if(!FIXREF&&resc){ asm volatile("s_waitcnt lgkmcnt(0)":::"memory"); \
;       _Pragma("unroll") for(int d_=0;d_<2;++d_) _Pragma("unroll") for(int r=0;r<16;++r)o[d_][r]*=wsf[crow(r,hi)]; } }while(0)
;   #define ROT() do{sl_prev=sl_cur;sl_cur=sl_next;sl_next=(sl_next==(NSLOT-1)*SLOTB)?0:sl_next+SLOTB;}while(0)
; template<int THRL,bool FIXREF,bool HALFK> __device__ __forceinline__ void attn_unit(float mref,long rowbase,int q0,const bf16*Qh,int PQ,const bf16*__restrict__ Kh_,int PK,const bf16*__restrict__ Vh_,int PV,bf16*Oh,int PO,const bf16*Gh,int PG,u32x4(&okeep)[4],int omode,float lam,float oml,const float ...
;     ...
;   for(;t+5<NT;t+=2){
;     STEP(pB0,pB1,pA0,pA1,t,true,true,true);     WAIT_BAR(2); RESC(); ROT();
;     STEP(pA0,pA1,pB0,pB1,t+1,true,true,true);   WAIT_BAR(2); RESC(); ROT();
;   }
.LBB0_451:
	v_add_u32_e32 v0, s66, v227
	ds_read_b64_tr_b16 v[234:235], v0 offset:24576
	ds_read_b64_tr_b16 v[236:237], v0 offset:25088
	v_add_f32_e32 v102, v82, v83
	v_add_f32_e32 v102, v84, v102
	v_add_f32_e32 v102, v85, v102
	v_add_f32_e32 v102, v86, v102
	v_add_f32_e32 v102, v87, v102
	v_cvt_pk_bf16_f32 v166, v82, v83
	v_cvt_pk_bf16_f32 v167, v84, v85
	s_waitcnt lgkmcnt(9)
	v_mfma_f32_32x32x16_bf16 v[114:129], v[98:101], v[174:177], v[50:65]
	ds_read_b64_tr_b16 v[82:83], v0 offset:28672
	ds_read_b64_tr_b16 v[84:85], v0 offset:29184
	v_add_f32_e32 v98, v88, v102
	v_add_f32_e32 v98, v89, v98
	v_add_f32_e32 v98, v90, v98
	v_add_f32_e32 v146, v91, v98
	s_waitcnt lgkmcnt(10)
	v_mfma_f32_32x32x16_bf16 v[98:113], v[182:185], v[174:177], v[50:65]
	v_cvt_pk_bf16_f32 v168, v86, v87
	v_cvt_pk_bf16_f32 v169, v88, v89
	ds_read_b64_tr_b16 v[86:87], v0 offset:25600
	ds_read_b64_tr_b16 v[88:89], v0 offset:26112
	v_add_f32_e32 v146, v92, v146
	v_add_f32_e32 v146, v93, v146
	v_add_f32_e32 v146, v94, v146
	v_add_f32_e32 v146, v95, v146
	v_cvt_pk_bf16_f32 v158, v90, v91
	v_cvt_pk_bf16_f32 v159, v92, v93
	s_waitcnt lgkmcnt(11)
	v_mfma_f32_32x32x16_bf16 v[114:129], v[186:189], v[170:173], v[114:129]
	ds_read_b64_tr_b16 v[90:91], v0 offset:29696
	ds_read_b64_tr_b16 v[92:93], v0 offset:30208
	s_waitcnt lgkmcnt(12)
	v_mfma_f32_32x32x16_bf16 v[98:113], v[178:181], v[170:173], v[98:113]
	v_add_f32_e32 v146, v96, v146
	v_add_f32_e32 v146, v97, v146
	v_add_f32_e32 v146, v66, v146
	v_add_f32_e32 v146, v67, v146
	v_cvt_pk_bf16_f32 v160, v94, v95
	v_cvt_pk_bf16_f32 v161, v96, v97
	ds_read_b64_tr_b16 v[94:95], v0 offset:26624
	ds_read_b64_tr_b16 v[96:97], v0 offset:27136
	s_waitcnt lgkmcnt(13)
	v_mfma_f32_32x32x16_bf16 v[114:129], v[142:145], v[162:165], v[114:129]
	v_add_f32_e32 v142, v68, v146
	v_add_f32_e32 v142, v69, v142
	v_add_f32_e32 v142, v70, v142
	v_add_f32_e32 v142, v71, v142
	v_cvt_pk_bf16_f32 v150, v66, v67
	v_cvt_pk_bf16_f32 v151, v68, v69
	ds_read_b64_tr_b16 v[66:67], v0 offset:30720
	ds_read_b64_tr_b16 v[68:69], v0 offset:31232
	s_waitcnt lgkmcnt(14)
	v_mfma_f32_32x32x16_bf16 v[98:113], v[138:141], v[162:165], v[98:113]
	v_add_f32_e32 v138, v72, v142
	v_add_f32_e32 v138, v73, v138
	v_add_f32_e32 v138, v74, v138
	v_add_f32_e32 v138, v75, v138
	v_cvt_pk_bf16_f32 v152, v70, v71
	v_cvt_pk_bf16_f32 v153, v72, v73
	ds_read_b64_tr_b16 v[70:71], v0 offset:27648
	ds_read_b64_tr_b16 v[72:73], v0 offset:28160
	s_waitcnt lgkmcnt(14)
	v_mfma_f32_32x32x16_bf16 v[114:129], v[134:137], v[154:157], v[114:129]
	v_add_f32_e32 v134, v76, v138
	v_add_f32_e32 v134, v77, v134
	v_add_f32_e32 v134, v78, v134
	v_add_f32_e32 v134, v79, v134
	v_cvt_pk_bf16_f32 v146, v74, v75
	v_cvt_pk_bf16_f32 v147, v76, v77
	ds_read_b64_tr_b16 v[74:75], v0 offset:31744
	ds_read_b64_tr_b16 v[76:77], v0 offset:32256
	v_mfma_f32_32x32x16_bf16 v[98:113], v[130:133], v[154:157], v[98:113]
	v_add_f32_e32 v0, v80, v134
	v_add_f32_e32 v0, v81, v0
	v_add_f32_e32 v0, 0, v0
	v_cvt_pk_bf16_f32 v148, v78, v79
	v_cvt_pk_bf16_f32 v149, v80, v81
	v_lshl_add_u64 v[78:79], v[214:215], 0, s[12:13]
	s_add_i32 s40, s65, s62
	s_mov_b32 s41, m0
	s_mov_b32 m0, s40
	s_nop 0
	global_load_lds_dwordx4 v[78:79], off
	s_mov_b32 m0, s41
	v_lshl_add_u64 v[78:79], v[212:213], 0, s[22:23]
	s_add_i32 s40, s49, s61
	s_mov_b32 s41, m0
	s_mov_b32 m0, s40
	s_nop 0
	global_load_lds_dwordx4 v[78:79], off
	s_mov_b32 m0, s41
	v_add_f32_e32 v0, v232, v0
	s_waitcnt lgkmcnt(14)
	v_mfma_f32_32x32x16_bf16 v[18:33], v[166:169], v[234:237], v[18:33]
	v_exp_f32_e32 v114, v114
	v_exp_f32_e32 v115, v115
	v_exp_f32_e32 v116, v116
	v_exp_f32_e32 v117, v117
	s_waitcnt lgkmcnt(12)
	v_mfma_f32_32x32x16_bf16 v[34:49], v[166:169], v[82:85], v[34:49]
	v_exp_f32_e32 v118, v118
	v_exp_f32_e32 v119, v119
	v_exp_f32_e32 v120, v120
	v_exp_f32_e32 v121, v121
	v_add_u32_e32 v82, s49, v228
	ds_read_b128 v[78:81], v82
	ds_read_b128 v[134:137], v82 offset:512
	s_waitcnt lgkmcnt(12)
	v_mfma_f32_32x32x16_bf16 v[18:33], v[158:161], v[86:89], v[18:33]
	v_exp_f32_e32 v122, v122
	v_exp_f32_e32 v123, v123
	v_exp_f32_e32 v124, v124
	v_exp_f32_e32 v125, v125
	ds_read_b128 v[138:141], v82 offset:2048
	ds_read_b128 v[142:145], v82 offset:2560
	s_waitcnt lgkmcnt(12)
	v_mfma_f32_32x32x16_bf16 v[34:49], v[158:161], v[90:93], v[34:49]
	v_exp_f32_e32 v126, v126
	v_exp_f32_e32 v127, v127
	v_exp_f32_e32 v128, v128
	v_exp_f32_e32 v129, v129
	ds_read_b128 v[178:181], v82 offset:4096
	ds_read_b128 v[182:185], v82 offset:4608
	s_waitcnt lgkmcnt(12)
	v_mfma_f32_32x32x16_bf16 v[18:33], v[150:153], v[94:97], v[18:33]
	v_exp_f32_e32 v98, v98
	v_exp_f32_e32 v99, v99
	v_exp_f32_e32 v100, v100
	v_exp_f32_e32 v101, v101
	ds_read_b128 v[186:189], v82 offset:6144
	ds_read_b128 v[130:133], v82 offset:6656
	s_waitcnt lgkmcnt(12)
	v_mfma_f32_32x32x16_bf16 v[34:49], v[150:153], v[66:69], v[34:49]
	v_exp_f32_e32 v102, v102
	v_exp_f32_e32 v103, v103
	v_exp_f32_e32 v104, v104
	v_exp_f32_e32 v105, v105
	s_waitcnt lgkmcnt(10)
	v_mfma_f32_32x32x16_bf16 v[18:33], v[146:149], v[70:73], v[18:33]
	v_exp_f32_e32 v106, v106
	v_exp_f32_e32 v107, v107
	v_exp_f32_e32 v108, v108
	v_exp_f32_e32 v109, v109
	s_waitcnt lgkmcnt(8)
	v_mfma_f32_32x32x16_bf16 v[34:49], v[146:149], v[74:77], v[34:49]
	v_exp_f32_e32 v110, v110
	v_exp_f32_e32 v111, v111
	v_exp_f32_e32 v112, v112
	v_exp_f32_e32 v113, v113
	s_add_i32 s40, s49, 0x2000
	s_cmpk_lg_i32 s49, 0x4000
	s_cselect_b32 s40, s40, 0
	v_add_u32_e32 v232, s65, v227
	s_waitcnt vmcnt(2) lgkmcnt(0)
	s_barrier
; #define WAIT_BAR(N) asm volatile("s_waitcnt vmcnt(" #N ") lgkmcnt(0)\n\ts_barrier":::"memory")
;   #define RESC() do{ if(!FIXREF&&resc){ asm volatile("s_waitcnt lgkmcnt(0)":::"memory"); \
;       _Pragma("unroll") for(int d_=0;d_<2;++d_) _Pragma("unroll") for(int r=0;r<16;++r)o[d_][r]*=wsf[crow(r,hi)]; } }while(0)
;   #define ROT() do{sl_prev=sl_cur;sl_cur=sl_next;sl_next=(sl_next==(NSLOT-1)*SLOTB)?0:sl_next+SLOTB;}while(0)
; template<int THRL,bool FIXREF,bool HALFK> __device__ __forceinline__ void attn_unit(float mref,long rowbase,int q0,const bf16*Qh,int PQ,const bf16*__restrict__ Kh_,int PK,const bf16*__restrict__ Vh_,int PV,bf16*Oh,int PO,const bf16*Gh,int PG,u32x4(&okeep)[4],int omode,float lam,float oml,const float ...
;     ...
;   for(;t+5<NT;t+=2){
;     STEP(pB0,pB1,pA0,pA1,t,true,true,true);     WAIT_BAR(2); RESC(); ROT();
;     STEP(pA0,pA1,pB0,pB1,t+1,true,true,true);   WAIT_BAR(2); RESC(); ROT();
;   }
	ds_read_b64_tr_b16 v[234:235], v232 offset:24576
	ds_read_b64_tr_b16 v[236:237], v232 offset:25088
	s_waitcnt lgkmcnt(9)
	v_mfma_f32_32x32x16_bf16 v[82:97], v[78:81], v[174:177], v[50:65]
	v_add_f32_e32 v66, v114, v115
	v_add_f32_e32 v66, v116, v66
	v_add_f32_e32 v66, v117, v66
	v_add_f32_e32 v66, v118, v66
	v_add_f32_e32 v66, v119, v66
	v_cvt_pk_bf16_f32 v166, v114, v115
	v_cvt_pk_bf16_f32 v167, v116, v117
	ds_read_b64_tr_b16 v[114:115], v232 offset:28672
	ds_read_b64_tr_b16 v[116:117], v232 offset:29184
	v_add_f32_e32 v66, v120, v66
	v_add_f32_e32 v66, v121, v66
	v_add_f32_e32 v66, v122, v66
	v_add_f32_e32 v146, v123, v66
	s_waitcnt lgkmcnt(10)
	v_mfma_f32_32x32x16_bf16 v[66:81], v[134:137], v[174:177], v[50:65]
	v_cvt_pk_bf16_f32 v168, v118, v119
	v_cvt_pk_bf16_f32 v169, v120, v121
	ds_read_b64_tr_b16 v[118:119], v232 offset:25600
	ds_read_b64_tr_b16 v[120:121], v232 offset:26112
	s_waitcnt lgkmcnt(11)
	v_mfma_f32_32x32x16_bf16 v[82:97], v[138:141], v[170:173], v[82:97]
	v_add_f32_e32 v134, v124, v146
	v_add_f32_e32 v134, v125, v134
	v_add_f32_e32 v134, v126, v134
	v_add_f32_e32 v134, v127, v134
	v_cvt_pk_bf16_f32 v158, v122, v123
	v_cvt_pk_bf16_f32 v159, v124, v125
	ds_read_b64_tr_b16 v[122:123], v232 offset:29696
	ds_read_b64_tr_b16 v[124:125], v232 offset:30208
	s_waitcnt lgkmcnt(12)
	v_mfma_f32_32x32x16_bf16 v[66:81], v[142:145], v[170:173], v[66:81]
	v_add_f32_e32 v134, v128, v134
	v_add_f32_e32 v134, v129, v134
	v_add_f32_e32 v134, v98, v134
	v_add_f32_e32 v134, v99, v134
	v_cvt_pk_bf16_f32 v160, v126, v127
	v_cvt_pk_bf16_f32 v161, v128, v129
	ds_read_b64_tr_b16 v[126:127], v232 offset:26624
	ds_read_b64_tr_b16 v[128:129], v232 offset:27136
	s_waitcnt lgkmcnt(13)
	v_mfma_f32_32x32x16_bf16 v[82:97], v[178:181], v[162:165], v[82:97]
	v_add_f32_e32 v134, v100, v134
	v_add_f32_e32 v134, v101, v134
	v_add_f32_e32 v134, v102, v134
	v_add_f32_e32 v134, v103, v134
	v_cvt_pk_bf16_f32 v150, v98, v99
	v_cvt_pk_bf16_f32 v151, v100, v101
	ds_read_b64_tr_b16 v[238:239], v232 offset:30720
	ds_read_b64_tr_b16 v[240:241], v232 offset:31232
	s_waitcnt lgkmcnt(14)
	v_mfma_f32_32x32x16_bf16 v[66:81], v[182:185], v[162:165], v[66:81]
	v_add_f32_e32 v98, v104, v134
	v_add_f32_e32 v98, v105, v98
	v_add_f32_e32 v98, v106, v98
	v_add_f32_e32 v98, v107, v98
	v_cvt_pk_bf16_f32 v152, v102, v103
	v_cvt_pk_bf16_f32 v153, v104, v105
	ds_read_b64_tr_b16 v[102:103], v232 offset:27648
	ds_read_b64_tr_b16 v[104:105], v232 offset:28160
	s_waitcnt lgkmcnt(14)
	v_mfma_f32_32x32x16_bf16 v[82:97], v[186:189], v[154:157], v[82:97]
	v_add_f32_e32 v98, v108, v98
	v_add_f32_e32 v98, v109, v98
	v_add_f32_e32 v98, v110, v98
	v_add_f32_e32 v98, v111, v98
	v_cvt_pk_bf16_f32 v146, v106, v107
	v_cvt_pk_bf16_f32 v147, v108, v109
	ds_read_b64_tr_b16 v[106:107], v232 offset:31744
	ds_read_b64_tr_b16 v[108:109], v232 offset:32256
	v_mfma_f32_32x32x16_bf16 v[66:81], v[130:133], v[154:157], v[66:81]
	v_add_f32_e32 v98, v112, v98
	v_add_f32_e32 v98, v113, v98
	v_add_f32_e32 v98, 0, v98
	v_cvt_pk_bf16_f32 v148, v110, v111
	v_cvt_pk_bf16_f32 v149, v112, v113
	s_nop 0
	v_add_f32_e32 v232, v0, v98
	v_lshl_add_u64 v[98:99], v[214:215], 0, s[92:93]
	s_add_i32 s41, s49, s62
	s_mov_b32 s42, m0
	s_mov_b32 m0, s41
	s_nop 0
	global_load_lds_dwordx4 v[98:99], off
	s_mov_b32 m0, s42
	v_lshl_add_u64 v[212:213], v[212:213], 0, s[4:5]
	s_add_i32 s41, s40, s61
	s_mov_b32 s42, m0
	s_mov_b32 m0, s41
	s_nop 0
	global_load_lds_dwordx4 v[212:213], off
	s_mov_b32 m0, s42
	s_waitcnt lgkmcnt(14)
	v_mfma_f32_32x32x16_bf16 v[18:33], v[166:169], v[234:237], v[18:33]
	v_exp_f32_e32 v82, v82
	v_exp_f32_e32 v83, v83
	v_exp_f32_e32 v84, v84
	v_exp_f32_e32 v85, v85
	s_waitcnt lgkmcnt(12)
	v_mfma_f32_32x32x16_bf16 v[34:49], v[166:169], v[114:117], v[34:49]
	v_exp_f32_e32 v86, v86
	v_exp_f32_e32 v87, v87
	v_exp_f32_e32 v88, v88
	v_exp_f32_e32 v89, v89
	v_add_u32_e32 v0, s40, v228
	ds_read_b128 v[98:101], v0
	ds_read_b128 v[182:185], v0 offset:512
	s_waitcnt lgkmcnt(12)
	v_mfma_f32_32x32x16_bf16 v[18:33], v[158:161], v[118:121], v[18:33]
	v_exp_f32_e32 v90, v90
	v_exp_f32_e32 v91, v91
	v_exp_f32_e32 v92, v92
	v_exp_f32_e32 v93, v93
	ds_read_b128 v[186:189], v0 offset:2048
	ds_read_b128 v[178:181], v0 offset:2560
	s_waitcnt lgkmcnt(12)
	v_mfma_f32_32x32x16_bf16 v[34:49], v[158:161], v[122:125], v[34:49]
	v_exp_f32_e32 v94, v94
	v_exp_f32_e32 v95, v95
	v_exp_f32_e32 v96, v96
	v_exp_f32_e32 v97, v97
	ds_read_b128 v[142:145], v0 offset:4096
	ds_read_b128 v[138:141], v0 offset:4608
	s_waitcnt lgkmcnt(12)
	v_mfma_f32_32x32x16_bf16 v[18:33], v[150:153], v[126:129], v[18:33]
	v_exp_f32_e32 v66, v66
	v_exp_f32_e32 v67, v67
	v_exp_f32_e32 v68, v68
	v_exp_f32_e32 v69, v69
	ds_read_b128 v[134:137], v0 offset:6144
	ds_read_b128 v[130:133], v0 offset:6656
	s_waitcnt lgkmcnt(12)
	v_mfma_f32_32x32x16_bf16 v[34:49], v[150:153], v[238:241], v[34:49]
	v_exp_f32_e32 v70, v70
	v_exp_f32_e32 v71, v71
	v_exp_f32_e32 v72, v72
	v_exp_f32_e32 v73, v73
	s_waitcnt lgkmcnt(10)
	v_mfma_f32_32x32x16_bf16 v[18:33], v[146:149], v[102:105], v[18:33]
	v_exp_f32_e32 v74, v74
	v_exp_f32_e32 v75, v75
	v_exp_f32_e32 v76, v76
	v_exp_f32_e32 v77, v77
	s_waitcnt lgkmcnt(8)
	v_mfma_f32_32x32x16_bf16 v[34:49], v[146:149], v[106:109], v[34:49]
	v_exp_f32_e32 v78, v78
	v_exp_f32_e32 v79, v79
	v_exp_f32_e32 v80, v80
	v_exp_f32_e32 v81, v81
	s_add_i32 s41, s40, 0x2000
	s_cmpk_lg_i32 s40, 0x4000
	s_mov_b32 s66, s49
	s_cselect_b32 s49, s41, 0
	s_add_i32 s48, s48, 2
	v_lshl_add_u64 v[214:215], v[214:215], 0, s[10:11]
	s_mov_b32 s65, s40
	s_cmp_gt_u32 s48, 56
	s_waitcnt vmcnt(2) lgkmcnt(0)
	s_barrier
	s_cbranch_scc0 .LBB0_451
;   #define RESC() do{ if(!FIXREF&&resc){ asm volatile("s_waitcnt lgkmcnt(0)":::"memory"); \
;       _Pragma("unroll") for(int d_=0;d_<2;++d_) _Pragma("unroll") for(int r=0;r<16;++r)o[d_][r]*=wsf[crow(r,hi)]; } }while(0)
;   #define ROT() do{sl_prev=sl_cur;sl_cur=sl_next;sl_next=(sl_next==(NSLOT-1)*SLOTB)?0:sl_next+SLOTB;}while(0)
;   #define ENDW(tt) do{ if((tt)+3<NT){WAIT_BAR(2);} else if((tt)+2<NT){WAIT_BAR(1);} else {WAIT_BAR(0);} }while(0)
; template<int THRL,bool FIXREF,bool HALFK> __device__ __forceinline__ void attn_unit(float mref,long rowbase,int q0,const bf16*Qh,int PQ,const bf16*__restrict__ Kh_,int PK,const bf16*__restrict__ Vh_,int PV,bf16*Oh,int PO,const bf16*Gh,int PG,u32x4(&okeep)[4],int omode,float lam,float oml,const float ...
;     ...
;   for(;t+1<NT;t+=2){
;     STEP(pB0,pB1,pA0,pA1,t,(t+3<NT),(t+1<NT),(t+1<NT));       ENDW(t);   RESC(); ROT();
;     STEP(pA0,pA1,pB0,pB1,t+1,(t+4<NT),(t+2<NT),(t+2<NT));     ENDW(t+1); RESC(); ROT();
	s_and_b32 s41, s64, 0x3fffffc0
	s_cmp_lg_u32 0, -1
	s_cselect_b32 s40, 0, 0
	s_add_i32 s42, s40, 0x6000
	v_add_u32_e32 v0, s42, v231
	s_lshl_b32 s41, s41, 2
	s_add_i32 s42, s41, 0
	v_add3_u32 v0, v0, v229, v230
	ds_read_b64_tr_b16 v[212:213], v227 offset:32768
	ds_read_b64_tr_b16 v[214:215], v227 offset:33280
	v_add_f32_e32 v102, v82, v83
	v_add_f32_e32 v102, v84, v102
	v_add_f32_e32 v102, v85, v102
	v_add_f32_e32 v102, v86, v102
	v_add_f32_e32 v102, v87, v102
	v_cvt_pk_bf16_f32 v166, v82, v83
	v_cvt_pk_bf16_f32 v167, v84, v85
	s_waitcnt lgkmcnt(9)
	v_mfma_f32_32x32x16_bf16 v[114:129], v[98:101], v[174:177], v[50:65]
	ds_read_b64_tr_b16 v[82:83], v227 offset:36864
	ds_read_b64_tr_b16 v[84:85], v227 offset:37376
	v_add_f32_e32 v98, v88, v102
	v_add_f32_e32 v98, v89, v98
	v_add_f32_e32 v98, v90, v98
	v_add_f32_e32 v146, v91, v98
	v_cvt_pk_bf16_f32 v168, v86, v87
	v_cvt_pk_bf16_f32 v169, v88, v89
	s_waitcnt lgkmcnt(10)
	v_mfma_f32_32x32x16_bf16 v[98:113], v[182:185], v[174:177], v[50:65]
	ds_read_b64_tr_b16 v[86:87], v227 offset:33792
	ds_read_b64_tr_b16 v[88:89], v227 offset:34304
	v_add_f32_e32 v146, v92, v146
	v_add_f32_e32 v146, v93, v146
	v_add_f32_e32 v146, v94, v146
	v_add_f32_e32 v146, v95, v146
	v_cvt_pk_bf16_f32 v158, v90, v91
	v_cvt_pk_bf16_f32 v159, v92, v93
	s_waitcnt lgkmcnt(11)
	v_mfma_f32_32x32x16_bf16 v[114:129], v[186:189], v[170:173], v[114:129]
	ds_read_b64_tr_b16 v[90:91], v227 offset:37888
	ds_read_b64_tr_b16 v[92:93], v227 offset:38400
	v_add_f32_e32 v146, v96, v146
	v_add_f32_e32 v146, v97, v146
	v_add_f32_e32 v146, v66, v146
	v_add_f32_e32 v146, v67, v146
	v_cvt_pk_bf16_f32 v160, v94, v95
	v_cvt_pk_bf16_f32 v161, v96, v97
	s_waitcnt lgkmcnt(12)
	v_mfma_f32_32x32x16_bf16 v[98:113], v[178:181], v[170:173], v[98:113]
	ds_read_b64_tr_b16 v[94:95], v227 offset:34816
	ds_read_b64_tr_b16 v[96:97], v227 offset:35328
	s_waitcnt lgkmcnt(13)
	v_mfma_f32_32x32x16_bf16 v[114:129], v[142:145], v[162:165], v[114:129]
	v_add_f32_e32 v142, v68, v146
	v_add_f32_e32 v142, v69, v142
	v_add_f32_e32 v142, v70, v142
	v_add_f32_e32 v142, v71, v142
	v_cvt_pk_bf16_f32 v150, v66, v67
	v_cvt_pk_bf16_f32 v151, v68, v69
	ds_read_b64_tr_b16 v[66:67], v227 offset:38912
	ds_read_b64_tr_b16 v[68:69], v227 offset:39424
	s_waitcnt lgkmcnt(14)
	v_mfma_f32_32x32x16_bf16 v[98:113], v[138:141], v[162:165], v[98:113]
	v_add_f32_e32 v138, v72, v142
	v_add_f32_e32 v138, v73, v138
	v_add_f32_e32 v138, v74, v138
	v_add_f32_e32 v138, v75, v138
	v_cvt_pk_bf16_f32 v152, v70, v71
	v_cvt_pk_bf16_f32 v153, v72, v73
	ds_read_b64_tr_b16 v[70:71], v227 offset:35840
	ds_read_b64_tr_b16 v[72:73], v227 offset:36352
	s_waitcnt lgkmcnt(14)
	v_mfma_f32_32x32x16_bf16 v[114:129], v[134:137], v[154:157], v[114:129]
	v_add_f32_e32 v134, v76, v138
	v_add_f32_e32 v134, v77, v134
	v_add_f32_e32 v134, v78, v134
	v_add_f32_e32 v134, v79, v134
	v_cvt_pk_bf16_f32 v146, v74, v75
	v_cvt_pk_bf16_f32 v147, v76, v77
	ds_read_b64_tr_b16 v[74:75], v227 offset:39936
	ds_read_b64_tr_b16 v[76:77], v227 offset:40448
	v_mfma_f32_32x32x16_bf16 v[98:113], v[130:133], v[154:157], v[98:113]
	v_add_f32_e32 v130, v80, v134
	v_add_f32_e32 v130, v81, v130
	v_add_f32_e32 v130, 0, v130
	v_cvt_pk_bf16_f32 v148, v78, v79
	v_cvt_pk_bf16_f32 v149, v80, v81
	s_mov_b64 s[46:47], 0xf8000
	s_add_i32 s40, s40, s63
	v_lshl_add_u64 v[78:79], v[210:211], 0, s[46:47]
	s_add_i32 s41, s40, 0x4000
	s_mov_b32 s43, m0
	s_mov_b32 m0, s41
	s_nop 0
	global_load_lds_dwordx4 v[78:79], off
	s_mov_b32 m0, s43
	v_lshl_add_u64 v[78:79], v[208:209], 0, s[18:19]
	s_mov_b32 s41, m0
	s_mov_b32 m0, s61
	s_nop 0
	global_load_lds_dwordx4 v[78:79], off
	s_mov_b32 m0, s41
	v_add_f32_e32 v229, v232, v130
	s_waitcnt lgkmcnt(14)
	v_mfma_f32_32x32x16_bf16 v[18:33], v[166:169], v[212:215], v[18:33]
	v_exp_f32_e32 v114, v114
	v_exp_f32_e32 v115, v115
	v_exp_f32_e32 v116, v116
	v_exp_f32_e32 v117, v117
	s_waitcnt lgkmcnt(12)
	v_mfma_f32_32x32x16_bf16 v[34:49], v[166:169], v[82:85], v[34:49]
	v_exp_f32_e32 v118, v118
	v_exp_f32_e32 v119, v119
	v_exp_f32_e32 v120, v120
	v_exp_f32_e32 v121, v121
	ds_read_b128 v[78:81], v228
	ds_read_b128 v[178:181], v228 offset:512
	s_waitcnt lgkmcnt(12)
	v_mfma_f32_32x32x16_bf16 v[18:33], v[158:161], v[86:89], v[18:33]
	v_exp_f32_e32 v122, v122
	v_exp_f32_e32 v123, v123
	v_exp_f32_e32 v124, v124
	v_exp_f32_e32 v125, v125
	ds_read_b128 v[86:89], v228 offset:2048
	ds_read_b128 v[182:185], v228 offset:2560
	s_waitcnt lgkmcnt(12)
	v_mfma_f32_32x32x16_bf16 v[34:49], v[158:161], v[90:93], v[34:49]
	v_exp_f32_e32 v126, v126
	v_exp_f32_e32 v127, v127
	v_exp_f32_e32 v128, v128
	v_exp_f32_e32 v129, v129
	ds_read_b128 v[90:93], v228 offset:4096
	ds_read_b128 v[186:189], v228 offset:4608
	s_waitcnt lgkmcnt(12)
	v_mfma_f32_32x32x16_bf16 v[18:33], v[150:153], v[94:97], v[18:33]
	v_exp_f32_e32 v98, v98
	v_exp_f32_e32 v99, v99
	v_exp_f32_e32 v100, v100
	v_exp_f32_e32 v101, v101
	ds_read_b128 v[94:97], v228 offset:6144
	ds_read_b128 v[82:85], v228 offset:6656
	s_waitcnt lgkmcnt(12)
	v_mfma_f32_32x32x16_bf16 v[34:49], v[150:153], v[66:69], v[34:49]
	v_exp_f32_e32 v102, v102
	v_exp_f32_e32 v103, v103
	v_exp_f32_e32 v104, v104
	v_exp_f32_e32 v105, v105
	s_waitcnt lgkmcnt(10)
	v_mfma_f32_32x32x16_bf16 v[18:33], v[146:149], v[70:73], v[18:33]
	v_exp_f32_e32 v106, v106
	v_exp_f32_e32 v107, v107
	v_exp_f32_e32 v108, v108
	v_exp_f32_e32 v109, v109
	s_waitcnt lgkmcnt(8)
	v_mfma_f32_32x32x16_bf16 v[34:49], v[146:149], v[74:77], v[34:49]
	v_exp_f32_e32 v110, v110
	v_exp_f32_e32 v111, v111
	v_exp_f32_e32 v112, v112
	v_exp_f32_e32 v113, v113
	s_waitcnt vmcnt(2) lgkmcnt(0)
	s_barrier
;   #define RESC() do{ if(!FIXREF&&resc){ asm volatile("s_waitcnt lgkmcnt(0)":::"memory"); \
;       _Pragma("unroll") for(int d_=0;d_<2;++d_) _Pragma("unroll") for(int r=0;r<16;++r)o[d_][r]*=wsf[crow(r,hi)]; } }while(0)
;   #define ROT() do{sl_prev=sl_cur;sl_cur=sl_next;sl_next=(sl_next==(NSLOT-1)*SLOTB)?0:sl_next+SLOTB;}while(0)
;   #define ENDW(tt) do{ if((tt)+3<NT){WAIT_BAR(2);} else if((tt)+2<NT){WAIT_BAR(1);} else {WAIT_BAR(0);} }while(0)
; template<int THRL,bool FIXREF,bool HALFK> __device__ __forceinline__ void attn_unit(float mref,long rowbase,int q0,const bf16*Qh,int PQ,const bf16*__restrict__ Kh_,int PK,const bf16*__restrict__ Vh_,int PV,bf16*Oh,int PO,const bf16*Gh,int PG,u32x4(&okeep)[4],int omode,float lam,float oml,const float ...
;     ...
;   for(;t+1<NT;t+=2){
;     STEP(pB0,pB1,pA0,pA1,t,(t+3<NT),(t+1<NT),(t+1<NT));       ENDW(t);   RESC(); ROT();
;     STEP(pA0,pA1,pB0,pB1,t+1,(t+4<NT),(t+2<NT),(t+2<NT));     ENDW(t+1); RESC(); ROT();
	ds_read_b64_tr_b16 v[212:213], v227 offset:40960
	ds_read_b64_tr_b16 v[214:215], v227 offset:41472
	v_add_f32_e32 v66, v114, v115
	v_add_f32_e32 v66, v116, v66
	v_add_f32_e32 v66, v117, v66
	v_add_f32_e32 v66, v118, v66
	v_add_f32_e32 v66, v119, v66
	v_cvt_pk_bf16_f32 v166, v114, v115
	v_cvt_pk_bf16_f32 v167, v116, v117
	s_waitcnt lgkmcnt(9)
	v_mfma_f32_32x32x16_bf16 v[130:145], v[78:81], v[174:177], v[50:65]
	ds_read_b64_tr_b16 v[114:115], v227 offset:45056
	ds_read_b64_tr_b16 v[116:117], v227 offset:45568
	v_add_f32_e32 v66, v120, v66
	v_add_f32_e32 v66, v121, v66
	v_add_f32_e32 v66, v122, v66
	v_add_f32_e32 v146, v123, v66
	s_waitcnt lgkmcnt(10)
	v_mfma_f32_32x32x16_bf16 v[66:81], v[178:181], v[174:177], v[50:65]
	v_cvt_pk_bf16_f32 v168, v118, v119
	v_cvt_pk_bf16_f32 v169, v120, v121
	ds_read_b64_tr_b16 v[118:119], v227 offset:41984
	ds_read_b64_tr_b16 v[120:121], v227 offset:42496
	s_waitcnt lgkmcnt(11)
	v_mfma_f32_32x32x16_bf16 v[130:145], v[86:89], v[170:173], v[130:145]
	v_add_f32_e32 v86, v124, v146
	v_add_f32_e32 v86, v125, v86
	v_add_f32_e32 v86, v126, v86
	v_add_f32_e32 v146, v127, v86
	v_cvt_pk_bf16_f32 v158, v122, v123
	v_cvt_pk_bf16_f32 v159, v124, v125
	ds_read_b64_tr_b16 v[86:87], v227 offset:46080
	ds_read_b64_tr_b16 v[88:89], v227 offset:46592
	s_waitcnt lgkmcnt(12)
	v_mfma_f32_32x32x16_bf16 v[66:81], v[182:185], v[170:173], v[66:81]
	v_add_f32_e32 v122, v128, v146
	v_add_f32_e32 v122, v129, v122
	v_add_f32_e32 v122, v98, v122
	v_add_f32_e32 v146, v99, v122
	v_cvt_pk_bf16_f32 v160, v126, v127
	v_cvt_pk_bf16_f32 v161, v128, v129
	ds_read_b64_tr_b16 v[122:123], v227 offset:43008
	ds_read_b64_tr_b16 v[124:125], v227 offset:43520
	s_waitcnt lgkmcnt(13)
	v_mfma_f32_32x32x16_bf16 v[130:145], v[90:93], v[162:165], v[130:145]
	v_add_f32_e32 v90, v100, v146
	v_add_f32_e32 v90, v101, v90
	v_add_f32_e32 v90, v102, v90
	v_add_f32_e32 v126, v103, v90
	v_cvt_pk_bf16_f32 v150, v98, v99
	v_cvt_pk_bf16_f32 v151, v100, v101
	ds_read_b64_tr_b16 v[90:91], v227 offset:47104
	ds_read_b64_tr_b16 v[92:93], v227 offset:47616
	s_waitcnt lgkmcnt(14)
	v_mfma_f32_32x32x16_bf16 v[66:81], v[186:189], v[162:165], v[66:81]
	v_add_f32_e32 v98, v104, v126
	v_add_f32_e32 v98, v105, v98
	v_add_f32_e32 v98, v106, v98
	v_add_f32_e32 v98, v107, v98
	v_cvt_pk_bf16_f32 v152, v102, v103
	v_cvt_pk_bf16_f32 v153, v104, v105
	ds_read_b64_tr_b16 v[102:103], v227 offset:44032
	ds_read_b64_tr_b16 v[104:105], v227 offset:44544
	s_waitcnt lgkmcnt(14)
	v_mfma_f32_32x32x16_bf16 v[130:145], v[94:97], v[154:157], v[130:145]
	v_add_f32_e32 v94, v108, v98
	v_add_f32_e32 v94, v109, v94
	v_add_f32_e32 v94, v110, v94
	v_add_f32_e32 v98, v111, v94
	v_cvt_pk_bf16_f32 v146, v106, v107
	v_cvt_pk_bf16_f32 v147, v108, v109
	ds_read_b64_tr_b16 v[94:95], v227 offset:48128
	ds_read_b64_tr_b16 v[96:97], v227 offset:48640
	v_mfma_f32_32x32x16_bf16 v[66:81], v[82:85], v[154:157], v[66:81]
	v_add_f32_e32 v82, v112, v98
	v_add_f32_e32 v82, v113, v82
	v_add_f32_e32 v82, 0, v82
	v_cvt_pk_bf16_f32 v148, v110, v111
	v_cvt_pk_bf16_f32 v149, v112, v113
	s_mov_b64 s[46:47], 0xfc000
	v_add_f32_e32 v229, v229, v82
	v_lshl_add_u64 v[82:83], v[210:211], 0, s[46:47]
	s_mov_b32 s41, m0
	s_mov_b32 m0, s62
	s_nop 0
	global_load_lds_dwordx4 v[82:83], off
	s_mov_b32 m0, s41
	v_lshl_add_u64 v[82:83], v[208:209], 0, s[6:7]
	s_add_i32 s41, s40, 0x8000
	s_mov_b32 s43, m0
	s_mov_b32 m0, s41
	s_nop 0
	global_load_lds_dwordx4 v[82:83], off
	s_mov_b32 m0, s43
	s_waitcnt lgkmcnt(14)
	v_mfma_f32_32x32x16_bf16 v[18:33], v[166:169], v[212:215], v[18:33]
	v_exp_f32_e32 v130, v130
	v_exp_f32_e32 v131, v131
	v_exp_f32_e32 v132, v132
	v_exp_f32_e32 v133, v133
	s_waitcnt lgkmcnt(12)
	v_mfma_f32_32x32x16_bf16 v[34:49], v[166:169], v[114:117], v[34:49]
	v_exp_f32_e32 v134, v134
	v_exp_f32_e32 v135, v135
	v_exp_f32_e32 v136, v136
	v_exp_f32_e32 v137, v137
	ds_read_b128 v[82:85], v228 offset:8192
	ds_read_b128 v[106:109], v228 offset:8704
	s_waitcnt lgkmcnt(12)
	v_mfma_f32_32x32x16_bf16 v[18:33], v[158:161], v[118:121], v[18:33]
	v_exp_f32_e32 v138, v138
	v_exp_f32_e32 v139, v139
	v_exp_f32_e32 v140, v140
	v_exp_f32_e32 v141, v141
	ds_read_b128 v[110:113], v228 offset:10240
	ds_read_b128 v[178:181], v228 offset:10752
	s_waitcnt lgkmcnt(12)
	v_mfma_f32_32x32x16_bf16 v[34:49], v[158:161], v[86:89], v[34:49]
	v_exp_f32_e32 v142, v142
	v_exp_f32_e32 v143, v143
	v_exp_f32_e32 v144, v144
	v_exp_f32_e32 v145, v145
	ds_read_b128 v[182:185], v228 offset:12288
	ds_read_b128 v[186:189], v228 offset:12800
	s_waitcnt lgkmcnt(12)
	v_mfma_f32_32x32x16_bf16 v[18:33], v[150:153], v[122:125], v[18:33]
	v_exp_f32_e32 v66, v66
	v_exp_f32_e32 v67, v67
	v_exp_f32_e32 v68, v68
	v_exp_f32_e32 v69, v69
	ds_read_b128 v[210:213], v228 offset:14336
	ds_read_b128 v[98:101], v228 offset:14848
	s_waitcnt lgkmcnt(12)
	v_mfma_f32_32x32x16_bf16 v[34:49], v[150:153], v[90:93], v[34:49]
	v_exp_f32_e32 v70, v70
	v_exp_f32_e32 v71, v71
	v_exp_f32_e32 v72, v72
	v_exp_f32_e32 v73, v73
	s_waitcnt lgkmcnt(10)
	v_mfma_f32_32x32x16_bf16 v[18:33], v[146:149], v[102:105], v[18:33]
	v_exp_f32_e32 v74, v74
	v_exp_f32_e32 v75, v75
	v_exp_f32_e32 v76, v76
	v_exp_f32_e32 v77, v77
	s_waitcnt lgkmcnt(8)
	v_mfma_f32_32x32x16_bf16 v[34:49], v[146:149], v[94:97], v[34:49]
	v_exp_f32_e32 v78, v78
	v_exp_f32_e32 v79, v79
	v_exp_f32_e32 v80, v80
	v_exp_f32_e32 v81, v81
	s_waitcnt vmcnt(2) lgkmcnt(0)
	s_barrier
;   #define RESC() do{ if(!FIXREF&&resc){ asm volatile("s_waitcnt lgkmcnt(0)":::"memory"); \
;       _Pragma("unroll") for(int d_=0;d_<2;++d_) _Pragma("unroll") for(int r=0;r<16;++r)o[d_][r]*=wsf[crow(r,hi)]; } }while(0)
;   #define ROT() do{sl_prev=sl_cur;sl_cur=sl_next;sl_next=(sl_next==(NSLOT-1)*SLOTB)?0:sl_next+SLOTB;}while(0)
;   #define ENDW(tt) do{ if((tt)+3<NT){WAIT_BAR(2);} else if((tt)+2<NT){WAIT_BAR(1);} else {WAIT_BAR(0);} }while(0)
; template<int THRL,bool FIXREF,bool HALFK> __device__ __forceinline__ void attn_unit(float mref,long rowbase,int q0,const bf16*Qh,int PQ,const bf16*__restrict__ Kh_,int PK,const bf16*__restrict__ Vh_,int PV,bf16*Oh,int PO,const bf16*Gh,int PG,u32x4(&okeep)[4],int omode,float lam,float oml,const float ...
;     ...
;   for(;t+1<NT;t+=2){
;     STEP(pB0,pB1,pA0,pA1,t,(t+3<NT),(t+1<NT),(t+1<NT));       ENDW(t);   RESC(); ROT();
;     STEP(pA0,pA1,pB0,pB1,t+1,(t+4<NT),(t+2<NT),(t+2<NT));     ENDW(t+1); RESC(); ROT();
	ds_read_b64_tr_b16 v[102:103], v227 offset:24576
	ds_read_b64_tr_b16 v[104:105], v227 offset:25088
	v_add_f32_e32 v86, v130, v131
	v_add_f32_e32 v86, v132, v86
	v_add_f32_e32 v86, v133, v86
	v_add_f32_e32 v86, v134, v86
	v_add_f32_e32 v86, v135, v86
	v_cvt_pk_bf16_f32 v166, v130, v131
	v_cvt_pk_bf16_f32 v167, v132, v133
	s_waitcnt lgkmcnt(9)
	v_mfma_f32_32x32x16_bf16 v[114:129], v[82:85], v[174:177], v[50:65]
	ds_read_b64_tr_b16 v[130:131], v227 offset:28672
	ds_read_b64_tr_b16 v[132:133], v227 offset:29184
	v_add_f32_e32 v82, v136, v86
	v_add_f32_e32 v82, v137, v82
	v_add_f32_e32 v82, v138, v82
	v_add_f32_e32 v146, v139, v82
	v_cvt_pk_bf16_f32 v168, v134, v135
	v_cvt_pk_bf16_f32 v169, v136, v137
	s_waitcnt lgkmcnt(10)
	v_mfma_f32_32x32x16_bf16 v[82:97], v[106:109], v[174:177], v[50:65]
	ds_read_b64_tr_b16 v[106:107], v227 offset:25600
	ds_read_b64_tr_b16 v[108:109], v227 offset:26112
	s_waitcnt lgkmcnt(11)
	v_mfma_f32_32x32x16_bf16 v[114:129], v[110:113], v[170:173], v[114:129]
	v_add_f32_e32 v110, v140, v146
	v_add_f32_e32 v110, v141, v110
	v_add_f32_e32 v110, v142, v110
	v_add_f32_e32 v134, v143, v110
	v_cvt_pk_bf16_f32 v158, v138, v139
	v_cvt_pk_bf16_f32 v159, v140, v141
	ds_read_b64_tr_b16 v[110:111], v227 offset:29696
	ds_read_b64_tr_b16 v[112:113], v227 offset:30208
	v_add_f32_e32 v134, v144, v134
	v_add_f32_e32 v134, v145, v134
	v_add_f32_e32 v134, v66, v134
	v_add_f32_e32 v138, v67, v134
	v_cvt_pk_bf16_f32 v160, v142, v143
	v_cvt_pk_bf16_f32 v161, v144, v145
	s_waitcnt lgkmcnt(12)
	v_mfma_f32_32x32x16_bf16 v[82:97], v[178:181], v[170:173], v[82:97]
	ds_read_b64_tr_b16 v[134:135], v227 offset:26624
	ds_read_b64_tr_b16 v[136:137], v227 offset:27136
	v_add_f32_e32 v138, v68, v138
	v_add_f32_e32 v138, v69, v138
	v_add_f32_e32 v138, v70, v138
	v_add_f32_e32 v138, v71, v138
	v_cvt_pk_bf16_f32 v150, v66, v67
	v_cvt_pk_bf16_f32 v151, v68, v69
	s_waitcnt lgkmcnt(13)
	v_mfma_f32_32x32x16_bf16 v[114:129], v[182:185], v[162:165], v[114:129]
	ds_read_b64_tr_b16 v[66:67], v227 offset:30720
	ds_read_b64_tr_b16 v[68:69], v227 offset:31232
	v_add_f32_e32 v138, v72, v138
	v_add_f32_e32 v138, v73, v138
	v_add_f32_e32 v138, v74, v138
	v_add_f32_e32 v138, v75, v138
	v_cvt_pk_bf16_f32 v152, v70, v71
	v_cvt_pk_bf16_f32 v153, v72, v73
	s_waitcnt lgkmcnt(14)
	v_mfma_f32_32x32x16_bf16 v[82:97], v[186:189], v[162:165], v[82:97]
	ds_read_b64_tr_b16 v[70:71], v227 offset:27648
	ds_read_b64_tr_b16 v[72:73], v227 offset:28160
	v_add_f32_e32 v138, v76, v138
	v_add_f32_e32 v138, v77, v138
	v_add_f32_e32 v138, v78, v138
	v_add_f32_e32 v138, v79, v138
	v_cvt_pk_bf16_f32 v146, v74, v75
	v_cvt_pk_bf16_f32 v147, v76, v77
	s_waitcnt lgkmcnt(14)
	v_mfma_f32_32x32x16_bf16 v[114:129], v[210:213], v[154:157], v[114:129]
	ds_read_b64_tr_b16 v[74:75], v227 offset:31744
	ds_read_b64_tr_b16 v[76:77], v227 offset:32256
	v_mfma_f32_32x32x16_bf16 v[82:97], v[98:101], v[154:157], v[82:97]
	v_add_f32_e32 v98, v80, v138
	v_add_f32_e32 v98, v81, v98
	v_add_f32_e32 v98, 0, v98
	v_cvt_pk_bf16_f32 v148, v78, v79
	v_cvt_pk_bf16_f32 v149, v80, v81
	v_lshl_add_u64 v[78:79], v[208:209], 0, s[94:95]
	s_add_i32 s40, s40, 0xa000
	s_mov_b32 s41, m0
	s_mov_b32 m0, s40
	s_nop 0
	global_load_lds_dwordx4 v[78:79], off
	s_mov_b32 m0, s41
	v_add_f32_e32 v214, v229, v98
	s_waitcnt lgkmcnt(14)
	v_mfma_f32_32x32x16_bf16 v[18:33], v[166:169], v[102:105], v[18:33]
	v_exp_f32_e32 v114, v114
	v_exp_f32_e32 v115, v115
	v_exp_f32_e32 v116, v116
	v_exp_f32_e32 v117, v117
	s_waitcnt lgkmcnt(12)
	v_mfma_f32_32x32x16_bf16 v[34:49], v[166:169], v[130:133], v[34:49]
	v_exp_f32_e32 v118, v118
	v_exp_f32_e32 v119, v119
	v_exp_f32_e32 v120, v120
	v_exp_f32_e32 v121, v121
	ds_read_b128 v[78:81], v228 offset:16384
	ds_read_b128 v[138:141], v228 offset:16896
	s_waitcnt lgkmcnt(12)
	v_mfma_f32_32x32x16_bf16 v[18:33], v[158:161], v[106:109], v[18:33]
	v_exp_f32_e32 v122, v122
	v_exp_f32_e32 v123, v123
	v_exp_f32_e32 v124, v124
	v_exp_f32_e32 v125, v125
	ds_read_b128 v[142:145], v228 offset:18432
	ds_read_b128 v[178:181], v228 offset:18944
	s_waitcnt lgkmcnt(12)
	v_mfma_f32_32x32x16_bf16 v[34:49], v[158:161], v[110:113], v[34:49]
	v_exp_f32_e32 v126, v126
	v_exp_f32_e32 v127, v127
	v_exp_f32_e32 v128, v128
	v_exp_f32_e32 v129, v129
	ds_read_b128 v[182:185], v228 offset:20480
	ds_read_b128 v[186:189], v228 offset:20992
	s_waitcnt lgkmcnt(12)
	v_mfma_f32_32x32x16_bf16 v[18:33], v[150:153], v[134:137], v[18:33]
	v_exp_f32_e32 v82, v82
	v_exp_f32_e32 v83, v83
	v_exp_f32_e32 v84, v84
	v_exp_f32_e32 v85, v85
	ds_read_b128 v[134:137], v228 offset:22528
	ds_read_b128 v[130:133], v228 offset:23040
	s_waitcnt lgkmcnt(12)
	v_mfma_f32_32x32x16_bf16 v[34:49], v[150:153], v[66:69], v[34:49]
	v_exp_f32_e32 v86, v86
	v_exp_f32_e32 v87, v87
	v_exp_f32_e32 v88, v88
	v_exp_f32_e32 v89, v89
	s_waitcnt lgkmcnt(10)
	v_mfma_f32_32x32x16_bf16 v[18:33], v[146:149], v[70:73], v[18:33]
	v_exp_f32_e32 v90, v90
	v_exp_f32_e32 v91, v91
	v_exp_f32_e32 v92, v92
	v_exp_f32_e32 v93, v93
	s_waitcnt lgkmcnt(8)
	v_mfma_f32_32x32x16_bf16 v[34:49], v[146:149], v[74:77], v[34:49]
	v_exp_f32_e32 v94, v94
	v_exp_f32_e32 v95, v95
	v_exp_f32_e32 v96, v96
	v_exp_f32_e32 v97, v97
	s_waitcnt vmcnt(1) lgkmcnt(0)
	s_barrier
;   #define RESC() do{ if(!FIXREF&&resc){ asm volatile("s_waitcnt lgkmcnt(0)":::"memory"); \
;       _Pragma("unroll") for(int d_=0;d_<2;++d_) _Pragma("unroll") for(int r=0;r<16;++r)o[d_][r]*=wsf[crow(r,hi)]; } }while(0)
;   #define ROT() do{sl_prev=sl_cur;sl_cur=sl_next;sl_next=(sl_next==(NSLOT-1)*SLOTB)?0:sl_next+SLOTB;}while(0)
;   #define ENDW(tt) do{ if((tt)+3<NT){WAIT_BAR(2);} else if((tt)+2<NT){WAIT_BAR(1);} else {WAIT_BAR(0);} }while(0)
; template<int THRL,bool FIXREF,bool HALFK> __device__ __forceinline__ void attn_unit(float mref,long rowbase,int q0,const bf16*Qh,int PQ,const bf16*__restrict__ Kh_,int PK,const bf16*__restrict__ Vh_,int PV,bf16*Oh,int PO,const bf16*Gh,int PG,u32x4(&okeep)[4],int omode,float lam,float oml,const float ...
;     ...
;   for(;t+1<NT;t+=2){
;     STEP(pB0,pB1,pA0,pA1,t,(t+3<NT),(t+1<NT),(t+1<NT));       ENDW(t);   RESC(); ROT();
;     STEP(pA0,pA1,pB0,pB1,t+1,(t+4<NT),(t+2<NT),(t+2<NT));     ENDW(t+1); RESC(); ROT();
	ds_read_b64_tr_b16 v[210:211], v227 offset:32768
	ds_read_b64_tr_b16 v[212:213], v227 offset:33280
	v_add_f32_e32 v66, v114, v115
	v_add_f32_e32 v66, v116, v66
	v_add_f32_e32 v66, v117, v66
	v_add_f32_e32 v66, v118, v66
	v_add_f32_e32 v66, v119, v66
	v_cvt_pk_bf16_f32 v166, v114, v115
	v_cvt_pk_bf16_f32 v167, v116, v117
	s_waitcnt lgkmcnt(9)
	v_mfma_f32_32x32x16_bf16 v[98:113], v[78:81], v[174:177], v[50:65]
	ds_read_b64_tr_b16 v[114:115], v227 offset:36864
	ds_read_b64_tr_b16 v[116:117], v227 offset:37376
	v_add_f32_e32 v66, v120, v66
	v_add_f32_e32 v66, v121, v66
	v_add_f32_e32 v66, v122, v66
	v_add_f32_e32 v146, v123, v66
	s_waitcnt lgkmcnt(10)
	v_mfma_f32_32x32x16_bf16 v[66:81], v[138:141], v[174:177], v[50:65]
	v_cvt_pk_bf16_f32 v168, v118, v119
	v_cvt_pk_bf16_f32 v169, v120, v121
	ds_read_b64_tr_b16 v[138:139], v227 offset:33792
	ds_read_b64_tr_b16 v[140:141], v227 offset:34304
	v_add_f32_e32 v118, v124, v146
	v_add_f32_e32 v118, v125, v118
	v_add_f32_e32 v118, v126, v118
	v_add_f32_e32 v118, v127, v118
	v_cvt_pk_bf16_f32 v158, v122, v123
	v_cvt_pk_bf16_f32 v159, v124, v125
	s_waitcnt lgkmcnt(11)
	v_mfma_f32_32x32x16_bf16 v[98:113], v[142:145], v[170:173], v[98:113]
	ds_read_b64_tr_b16 v[120:121], v227 offset:37888
	ds_read_b64_tr_b16 v[122:123], v227 offset:38400
	s_waitcnt lgkmcnt(12)
	v_mfma_f32_32x32x16_bf16 v[66:81], v[178:181], v[170:173], v[66:81]
	v_add_f32_e32 v118, v128, v118
	v_add_f32_e32 v118, v129, v118
	v_add_f32_e32 v118, v82, v118
	v_add_f32_e32 v118, v83, v118
	v_cvt_pk_bf16_f32 v160, v126, v127
	v_cvt_pk_bf16_f32 v161, v128, v129
	ds_read_b64_tr_b16 v[124:125], v227 offset:34816
	ds_read_b64_tr_b16 v[126:127], v227 offset:35328
	v_add_f32_e32 v118, v84, v118
	v_add_f32_e32 v118, v85, v118
	v_add_f32_e32 v118, v86, v118
	v_add_f32_e32 v118, v87, v118
	v_cvt_pk_bf16_f32 v150, v82, v83
	v_cvt_pk_bf16_f32 v151, v84, v85
	s_waitcnt lgkmcnt(13)
	v_mfma_f32_32x32x16_bf16 v[98:113], v[182:185], v[162:165], v[98:113]
	ds_read_b64_tr_b16 v[82:83], v227 offset:38912
	ds_read_b64_tr_b16 v[84:85], v227 offset:39424
	s_waitcnt lgkmcnt(14)
	v_mfma_f32_32x32x16_bf16 v[66:81], v[186:189], v[162:165], v[66:81]
	v_add_f32_e32 v118, v88, v118
	v_add_f32_e32 v118, v89, v118
	v_add_f32_e32 v118, v90, v118
	v_add_f32_e32 v118, v91, v118
	v_cvt_pk_bf16_f32 v152, v86, v87
	v_cvt_pk_bf16_f32 v153, v88, v89
	ds_read_b64_tr_b16 v[86:87], v227 offset:35840
	ds_read_b64_tr_b16 v[88:89], v227 offset:36352
	v_add_f32_e32 v118, v92, v118
	v_add_f32_e32 v118, v93, v118
	v_add_f32_e32 v118, v94, v118
	v_add_f32_e32 v118, v95, v118
	v_cvt_pk_bf16_f32 v146, v90, v91
	v_cvt_pk_bf16_f32 v147, v92, v93
	s_waitcnt lgkmcnt(14)
	v_mfma_f32_32x32x16_bf16 v[98:113], v[134:137], v[154:157], v[98:113]
	ds_read_b64_tr_b16 v[90:91], v227 offset:39936
	ds_read_b64_tr_b16 v[92:93], v227 offset:40448
	v_mfma_f32_32x32x16_bf16 v[66:81], v[130:133], v[154:157], v[66:81]
	v_add_f32_e32 v118, v96, v118
	v_add_f32_e32 v118, v97, v118
	v_add_f32_e32 v118, 0, v118
	v_cvt_pk_bf16_f32 v148, v94, v95
	v_cvt_pk_bf16_f32 v149, v96, v97
	v_lshl_add_u64 v[94:95], v[208:209], 0, s[26:27]
	s_mov_b32 s40, m0
	s_mov_b32 m0, s61
	s_nop 0
	global_load_lds_dwordx4 v[94:95], off
	s_mov_b32 m0, s40
	v_add_f32_e32 v118, v214, v118
	s_waitcnt lgkmcnt(14)
	v_mfma_f32_32x32x16_bf16 v[18:33], v[166:169], v[210:213], v[18:33]
	v_exp_f32_e32 v98, v98
	v_exp_f32_e32 v99, v99
	v_exp_f32_e32 v100, v100
	v_exp_f32_e32 v101, v101
	s_waitcnt lgkmcnt(12)
	v_mfma_f32_32x32x16_bf16 v[34:49], v[166:169], v[114:117], v[34:49]
	v_exp_f32_e32 v102, v102
	v_exp_f32_e32 v103, v103
	v_exp_f32_e32 v104, v104
	v_exp_f32_e32 v105, v105
	ds_read_b128 v[128:131], v228
	ds_read_b128 v[132:135], v228 offset:512
	s_waitcnt lgkmcnt(12)
	v_mfma_f32_32x32x16_bf16 v[18:33], v[158:161], v[138:141], v[18:33]
	v_exp_f32_e32 v106, v106
	v_exp_f32_e32 v107, v107
	v_exp_f32_e32 v108, v108
	v_exp_f32_e32 v109, v109
	ds_read_b128 v[136:139], v228 offset:2048
	ds_read_b128 v[140:143], v228 offset:2560
	s_waitcnt lgkmcnt(12)
	v_mfma_f32_32x32x16_bf16 v[34:49], v[158:161], v[120:123], v[34:49]
	v_exp_f32_e32 v110, v110
	v_exp_f32_e32 v111, v111
	v_exp_f32_e32 v112, v112
	v_exp_f32_e32 v113, v113
	ds_read_b128 v[120:123], v228 offset:4096
	ds_read_b128 v[178:181], v228 offset:4608
	s_waitcnt lgkmcnt(12)
	v_mfma_f32_32x32x16_bf16 v[18:33], v[150:153], v[124:127], v[18:33]
	v_exp_f32_e32 v66, v66
	v_exp_f32_e32 v67, v67
	v_exp_f32_e32 v68, v68
	v_exp_f32_e32 v69, v69
	ds_read_b128 v[124:127], v228 offset:6144
	ds_read_b128 v[114:117], v228 offset:6656
	s_waitcnt lgkmcnt(12)
	v_mfma_f32_32x32x16_bf16 v[34:49], v[150:153], v[82:85], v[34:49]
	v_exp_f32_e32 v70, v70
	v_exp_f32_e32 v71, v71
	v_exp_f32_e32 v72, v72
	v_exp_f32_e32 v73, v73
	s_waitcnt lgkmcnt(10)
	v_mfma_f32_32x32x16_bf16 v[18:33], v[146:149], v[86:89], v[18:33]
	v_exp_f32_e32 v74, v74
	v_exp_f32_e32 v75, v75
	v_exp_f32_e32 v76, v76
	v_exp_f32_e32 v77, v77
	s_waitcnt lgkmcnt(8)
	v_mfma_f32_32x32x16_bf16 v[34:49], v[146:149], v[90:93], v[34:49]
	v_exp_f32_e32 v78, v78
	v_exp_f32_e32 v79, v79
	v_exp_f32_e32 v80, v80
	v_exp_f32_e32 v81, v81
	s_waitcnt vmcnt(0) lgkmcnt(0)
	s_barrier
;   #define RESC() do{ if(!FIXREF&&resc){ asm volatile("s_waitcnt lgkmcnt(0)":::"memory"); \
;       _Pragma("unroll") for(int d_=0;d_<2;++d_) _Pragma("unroll") for(int r=0;r<16;++r)o[d_][r]*=wsf[crow(r,hi)]; } }while(0)
; template<int THRL,bool FIXREF,bool HALFK> __device__ __forceinline__ void attn_unit(float mref,long rowbase,int q0,const bf16*Qh,int PQ,const bf16*__restrict__ Kh_,int PK,const bf16*__restrict__ Vh_,int PV,bf16*Oh,int PO,const bf16*Gh,int PG,u32x4(&okeep)[4],int omode,float lam,float oml,const float ...
;     ...
;   STEP(pB0,pB1,pA0,pA1,NT-1,false,false,false); RESC();
	ds_read_b64_tr_b16 v[182:183], v227 offset:40960
	ds_read_b64_tr_b16 v[184:185], v227 offset:41472
	v_add_f32_e32 v82, v98, v99
	v_add_f32_e32 v82, v100, v82
	v_add_f32_e32 v82, v101, v82
	v_add_f32_e32 v82, v102, v82
	v_add_f32_e32 v119, v103, v82
	v_cvt_pk_bf16_f32 v166, v98, v99
	v_cvt_pk_bf16_f32 v167, v100, v101
	s_waitcnt lgkmcnt(9)
	v_mfma_f32_32x32x16_bf16 v[82:97], v[128:131], v[174:177], v[50:65]
	ds_read_b64_tr_b16 v[98:99], v227 offset:45056
	ds_read_b64_tr_b16 v[100:101], v227 offset:45568
	v_add_f32_e32 v119, v104, v119
	v_add_f32_e32 v119, v105, v119
	v_add_f32_e32 v119, v106, v119
	v_add_f32_e32 v119, v107, v119
	v_cvt_pk_bf16_f32 v168, v102, v103
	v_cvt_pk_bf16_f32 v169, v104, v105
	s_waitcnt lgkmcnt(10)
	v_mfma_f32_32x32x16_bf16 v[50:65], v[132:135], v[174:177], v[50:65]
	ds_read_b64_tr_b16 v[102:103], v227 offset:41984
	ds_read_b64_tr_b16 v[104:105], v227 offset:42496
	v_add_f32_e32 v119, v108, v119
	v_add_f32_e32 v119, v109, v119
	v_add_f32_e32 v119, v110, v119
	v_add_f32_e32 v119, v111, v119
	v_cvt_pk_bf16_f32 v158, v106, v107
	v_cvt_pk_bf16_f32 v159, v108, v109
	s_waitcnt lgkmcnt(11)
	v_mfma_f32_32x32x16_bf16 v[82:97], v[136:139], v[170:173], v[82:97]
	ds_read_b64_tr_b16 v[106:107], v227 offset:46080
	ds_read_b64_tr_b16 v[108:109], v227 offset:46592
	v_add_f32_e32 v119, v112, v119
	v_add_f32_e32 v119, v113, v119
	v_add_f32_e32 v119, v66, v119
	v_add_f32_e32 v119, v67, v119
	v_cvt_pk_bf16_f32 v160, v110, v111
	v_cvt_pk_bf16_f32 v161, v112, v113
	s_waitcnt lgkmcnt(12)
	v_mfma_f32_32x32x16_bf16 v[50:65], v[140:143], v[170:173], v[50:65]
	ds_read_b64_tr_b16 v[110:111], v227 offset:43008
	ds_read_b64_tr_b16 v[112:113], v227 offset:43520
	v_add_f32_e32 v119, v68, v119
	v_add_f32_e32 v119, v69, v119
	v_add_f32_e32 v119, v70, v119
	v_add_f32_e32 v119, v71, v119
	v_cvt_pk_bf16_f32 v150, v66, v67
	v_cvt_pk_bf16_f32 v151, v68, v69
	s_waitcnt lgkmcnt(13)
	v_mfma_f32_32x32x16_bf16 v[82:97], v[120:123], v[162:165], v[82:97]
	ds_read_b64_tr_b16 v[66:67], v227 offset:47104
	ds_read_b64_tr_b16 v[68:69], v227 offset:47616
	v_add_f32_e32 v119, v72, v119
	v_add_f32_e32 v119, v73, v119
	v_add_f32_e32 v119, v74, v119
	v_add_f32_e32 v119, v75, v119
	v_cvt_pk_bf16_f32 v152, v70, v71
	v_cvt_pk_bf16_f32 v153, v72, v73
	s_waitcnt lgkmcnt(14)
	v_mfma_f32_32x32x16_bf16 v[50:65], v[178:181], v[162:165], v[50:65]
	ds_read_b64_tr_b16 v[70:71], v227 offset:44032
	ds_read_b64_tr_b16 v[72:73], v227 offset:44544
	v_add_f32_e32 v119, v76, v119
	v_add_f32_e32 v119, v77, v119
	v_add_f32_e32 v119, v78, v119
	v_add_f32_e32 v119, v79, v119
	v_cvt_pk_bf16_f32 v146, v74, v75
	v_cvt_pk_bf16_f32 v147, v76, v77
	s_waitcnt lgkmcnt(14)
	v_mfma_f32_32x32x16_bf16 v[82:97], v[124:127], v[154:157], v[82:97]
	ds_read_b64_tr_b16 v[74:75], v227 offset:48128
	ds_read_b64_tr_b16 v[76:77], v227 offset:48640
	v_mfma_f32_32x32x16_bf16 v[50:65], v[114:117], v[154:157], v[50:65]
	v_add_f32_e32 v114, v80, v119
	v_add_f32_e32 v114, v81, v114
	v_add_f32_e32 v114, 0, v114
	v_cvt_pk_bf16_f32 v148, v78, v79
	v_cvt_pk_bf16_f32 v149, v80, v81
	s_waitcnt lgkmcnt(14)
	v_mfma_f32_32x32x16_bf16 v[18:33], v[166:169], v[182:185], v[18:33]
	s_nop 1
	v_exp_f32_e32 v82, v82
	v_exp_f32_e32 v83, v83
	v_exp_f32_e32 v84, v84
	v_exp_f32_e32 v85, v85
	s_waitcnt lgkmcnt(12)
	v_mfma_f32_32x32x16_bf16 v[34:49], v[166:169], v[98:101], v[34:49]
	v_exp_f32_e32 v86, v86
	v_exp_f32_e32 v87, v87
	v_exp_f32_e32 v88, v88
	v_exp_f32_e32 v89, v89
	s_waitcnt lgkmcnt(10)
	v_mfma_f32_32x32x16_bf16 v[18:33], v[158:161], v[102:105], v[18:33]
	v_exp_f32_e32 v90, v90
	v_exp_f32_e32 v91, v91
	v_exp_f32_e32 v92, v92
	v_exp_f32_e32 v93, v93
	s_waitcnt lgkmcnt(8)
	v_mfma_f32_32x32x16_bf16 v[34:49], v[158:161], v[106:109], v[34:49]
	v_exp_f32_e32 v94, v94
	v_exp_f32_e32 v95, v95
	v_exp_f32_e32 v96, v96
	v_exp_f32_e32 v97, v97
	s_waitcnt lgkmcnt(6)
; #define SBAR() __builtin_amdgcn_sched_barrier(0)
;   #define RESC() do{ if(!FIXREF&&resc){ asm volatile("s_waitcnt lgkmcnt(0)":::"memory"); \
;       _Pragma("unroll") for(int d_=0;d_<2;++d_) _Pragma("unroll") for(int r=0;r<16;++r)o[d_][r]*=wsf[crow(r,hi)]; } }while(0)
;   #define PKW(P,B) cvtpk_s(P[B],P[B+1])
; __device__ __forceinline__ void pv(f32x16*o,int vb,bf16x8 pa0,bf16x8 pa1,bf16x8 pa2,bf16x8 pa3){
;   #pragma unroll
;   for(int d0=0;d0<2;++d0){s16x4 lo[4],hi[4];
;     #pragma unroll
;     for(int ks=0;ks<4;++ks){
;       asm volatile("ds_read_b64_tr_b16 %0,%1 offset:%c2":"=&v"(lo[ks]):"v"(vb),"i"(d0*4096+ks*1024):"memory");
;       asm volatile("ds_read_b64_tr_b16 %0,%1 offset:%c2":"=&v"(hi[ks]):"v"(vb),"i"(d0*4096+ks*1024+512):"memory");}
;     asm volatile("s_waitcnt lgkmcnt(0)":::"memory");SBAR();
;     ...
;     o[d0]=__builtin_amdgcn_mfma_f32_32x32x16_bf16(pa0,PK(0),o[d0],0,0,0);
;     o[d0]=__builtin_amdgcn_mfma_f32_32x32x16_bf16(pa1,PK(1),o[d0],0,0,0);
;     o[d0]=__builtin_amdgcn_mfma_f32_32x32x16_bf16(pa2,PK(2),o[d0],0,0,0);
;     o[d0]=__builtin_amdgcn_mfma_f32_32x32x16_bf16(pa3,PK(3),o[d0],0,0,0);
;     ...
;   }
; template<int THRL,bool FIXREF,bool HALFK> __device__ __forceinline__ void attn_unit(float mref,long rowbase,int q0,const bf16*Qh,int PQ,const bf16*__restrict__ Kh_,int PK,const bf16*__restrict__ Vh_,int PV,bf16*Oh,int PO,const bf16*Gh,int PG,u32x4(&okeep)[4],int omode,float lam,float oml,const float ...
;     ...
;   STEP(pB0,pB1,pA0,pA1,NT-1,false,false,false); RESC();
;   { float sacc=pB0[0]+pB0[1]; _Pragma("unroll") for(int r=2;r<16;++r)sacc+=pB0[r]; _Pragma("unroll") for(int r=0;r<16;++r)sacc+=pB1[r]; l_reg+=sacc;
;     pw0=(u32x4){PKW(pB0,0),PKW(pB0,2),PKW(pB0,4),PKW(pB0,6)};pw1=(u32x4){PKW(pB0,8),PKW(pB0,10),PKW(pB0,12),PKW(pB0,14)};pw2=(u32x4){PKW(pB1,0),PKW(pB1,2),PKW(pB1,4),PKW(pB1,6)};pw3=(u32x4){PKW(pB1,8),PKW(pB1,10),PKW(pB1,12),PKW(pB1,14)};
;     SBAR(); pv(o,vb0+sl_cur,PAF(0),PAF(1),PAF(2),PAF(3)); }
;     ...
;   {auto rr=__builtin_amdgcn_permlane32_swap(__float_as_uint(l_reg),__float_as_uint(l_reg),false,false);l_reg=__uint_as_float(rr[0])+__uint_as_float(rr[1]);}
;   if(hi==0)wsf[32+r32]=l_reg;asm volatile("s_waitcnt lgkmcnt(0)":::"memory");
	v_mfma_f32_32x32x16_bf16 v[18:33], v[150:153], v[110:113], v[18:33]
	v_exp_f32_e32 v50, v50
	v_exp_f32_e32 v51, v51
	v_exp_f32_e32 v52, v52
	v_exp_f32_e32 v53, v53
	s_waitcnt lgkmcnt(4)
	v_mfma_f32_32x32x16_bf16 v[34:49], v[150:153], v[66:69], v[34:49]
	v_exp_f32_e32 v54, v54
	v_exp_f32_e32 v55, v55
	v_exp_f32_e32 v56, v56
	v_exp_f32_e32 v57, v57
	s_waitcnt lgkmcnt(2)
	v_mfma_f32_32x32x16_bf16 v[18:33], v[146:149], v[70:73], v[18:33]
	v_exp_f32_e32 v58, v58
	v_exp_f32_e32 v59, v59
	v_exp_f32_e32 v60, v60
	v_exp_f32_e32 v61, v61
	s_waitcnt lgkmcnt(0)
	v_mfma_f32_32x32x16_bf16 v[34:49], v[146:149], v[74:77], v[34:49]
	v_exp_f32_e32 v62, v62
	v_exp_f32_e32 v63, v63
	v_exp_f32_e32 v64, v64
	v_exp_f32_e32 v65, v65
	v_add_f32_e32 v66, v82, v83
	v_add_f32_e32 v66, v84, v66
	v_add_f32_e32 v66, v85, v66
	v_add_f32_e32 v66, v86, v66
	v_add_f32_e32 v66, v87, v66
	v_add_f32_e32 v66, v88, v66
	v_add_f32_e32 v66, v89, v66
	v_add_f32_e32 v66, v90, v66
	v_add_f32_e32 v66, v91, v66
	v_add_f32_e32 v66, v92, v66
	v_add_f32_e32 v66, v93, v66
	v_add_f32_e32 v66, v94, v66
	v_add_f32_e32 v66, v95, v66
	v_add_f32_e32 v66, v96, v66
	v_add_f32_e32 v66, v97, v66
	v_add_f32_e32 v66, v50, v66
	v_add_f32_e32 v66, v51, v66
	v_add_f32_e32 v66, v52, v66
	v_add_f32_e32 v66, v53, v66
	v_add_f32_e32 v66, v54, v66
	v_add_f32_e32 v66, v55, v66
	v_add_f32_e32 v66, v56, v66
	v_add_f32_e32 v66, v57, v66
	v_add_f32_e32 v66, v58, v66
	v_add_f32_e32 v66, v59, v66
	v_add_f32_e32 v66, v60, v66
	v_add_f32_e32 v66, v61, v66
	v_add_f32_e32 v66, v62, v66
	v_add_f32_e32 v66, v63, v66
	v_add_f32_e32 v66, v64, v66
	v_add_f32_e32 v66, v65, v66
	v_add_f32_e32 v67, v118, v114
	v_add_f32_e32 v66, v67, v66
	v_cvt_pk_bf16_f32 v68, v82, v83
	v_cvt_pk_bf16_f32 v69, v84, v85
	v_cvt_pk_bf16_f32 v70, v86, v87
	v_cvt_pk_bf16_f32 v71, v88, v89
	v_cvt_pk_bf16_f32 v72, v90, v91
	v_cvt_pk_bf16_f32 v73, v92, v93
	v_cvt_pk_bf16_f32 v74, v94, v95
	v_cvt_pk_bf16_f32 v75, v96, v97
	v_cvt_pk_bf16_f32 v50, v50, v51
	v_cvt_pk_bf16_f32 v51, v52, v53
	v_cvt_pk_bf16_f32 v52, v54, v55
	v_cvt_pk_bf16_f32 v53, v56, v57
	v_cvt_pk_bf16_f32 v54, v58, v59
	v_cvt_pk_bf16_f32 v55, v60, v61
	v_cvt_pk_bf16_f32 v56, v62, v63
	v_cvt_pk_bf16_f32 v57, v64, v65
	ds_read_b64_tr_b16 v[58:59],v0 offset:0
	ds_read_b64_tr_b16 v[60:61],v0 offset:512
	ds_read_b64_tr_b16 v[62:63],v0 offset:1024
	ds_read_b64_tr_b16 v[64:65],v0 offset:1536
	ds_read_b64_tr_b16 v[76:77],v0 offset:2048
	ds_read_b64_tr_b16 v[78:79],v0 offset:2560
	ds_read_b64_tr_b16 v[80:81],v0 offset:3072
	ds_read_b64_tr_b16 v[82:83],v0 offset:3584
	s_waitcnt lgkmcnt(0)
	s_nop 0
	v_mfma_f32_32x32x16_bf16 v[18:33], v[68:71], v[58:61], v[18:33]
	ds_read_b64_tr_b16 v[58:59],v0 offset:4096
	ds_read_b64_tr_b16 v[60:61],v0 offset:4608
	v_mfma_f32_32x32x16_bf16 v[18:33], v[72:75], v[62:65], v[18:33]
	ds_read_b64_tr_b16 v[62:63],v0 offset:5120
	ds_read_b64_tr_b16 v[64:65],v0 offset:5632
	v_mfma_f32_32x32x16_bf16 v[18:33], v[50:53], v[76:79], v[18:33]
	ds_read_b64_tr_b16 v[76:77],v0 offset:6144
	ds_read_b64_tr_b16 v[78:79],v0 offset:6656
	v_mfma_f32_32x32x16_bf16 v[18:33], v[54:57], v[80:83], v[18:33]
	ds_read_b64_tr_b16 v[80:81],v0 offset:7168
	ds_read_b64_tr_b16 v[82:83],v0 offset:7680
	s_waitcnt lgkmcnt(0)
	v_mfma_f32_32x32x16_bf16 v[34:49], v[68:71], v[58:61], v[34:49]
	v_mov_b32_e32 v0, v66
	s_nop 1
	v_permlane32_swap_b32_e32 v66, v0
	v_cmp_gt_u32_e32 vcc, 32, v205
	v_mfma_f32_32x32x16_bf16 v[34:49], v[72:75], v[62:65], v[34:49]
	v_mfma_f32_32x32x16_bf16 v[34:49], v[50:53], v[76:79], v[34:49]
	v_mfma_f32_32x32x16_bf16 v[34:49], v[54:57], v[80:83], v[34:49]
	s_and_saveexec_b64 s[40:41], vcc
	s_cbranch_execz .LBB0_449
	v_lshl_add_u32 v50, v216, 2, s42
	v_add_f32_e32 v0, v66, v0
	ds_write_b32 v50, v0 offset:49280
	s_branch .LBB0_449

; #define WAIT_BAR(N) asm volatile("s_waitcnt vmcnt(" #N ") lgkmcnt(0)\n\ts_barrier":::"memory")
;   #define RESC() do{ if(!FIXREF&&resc){ asm volatile("s_waitcnt lgkmcnt(0)":::"memory"); \
;       _Pragma("unroll") for(int d_=0;d_<2;++d_) _Pragma("unroll") for(int r=0;r<16;++r)o[d_][r]*=wsf[crow(r,hi)]; } }while(0)
;   #define ROT() do{sl_prev=sl_cur;sl_cur=sl_next;sl_next=(sl_next==(NSLOT-1)*SLOTB)?0:sl_next+SLOTB;}while(0)
; template<int THRL,bool FIXREF,bool HALFK> __device__ __forceinline__ void attn_unit(float mref,long rowbase,int q0,const bf16*Qh,int PQ,const bf16*__restrict__ Kh_,int PK,const bf16*__restrict__ Vh_,int PV,bf16*Oh,int PO,const bf16*Gh,int PG,u32x4(&okeep)[4],int omode,float lam,float oml,const float ...
;     ...
;   for(;t+5<NT;t+=2){
;     STEP(pB0,pB1,pA0,pA1,t,true,true,true);     WAIT_BAR(2); RESC(); ROT();
;     STEP(pA0,pA1,pB0,pB1,t+1,true,true,true);   WAIT_BAR(2); RESC(); ROT();
;   }
.LBB0_461:
	v_add_u32_e32 v0, s87, v213
	ds_read_b64_tr_b16 v[228:229], v0 offset:24576
	ds_read_b64_tr_b16 v[230:231], v0 offset:25088
	v_add_f32_e32 v102, v82, v83
	v_add_f32_e32 v102, v84, v102
	v_add_f32_e32 v102, v85, v102
	v_add_f32_e32 v102, v86, v102
	v_add_f32_e32 v102, v87, v102
	v_cvt_pk_bf16_f32 v158, v82, v83
	v_cvt_pk_bf16_f32 v159, v84, v85
	s_waitcnt lgkmcnt(5)
	v_mfma_f32_32x32x16_bf16 v[114:129], v[98:101], v[166:169], v[50:65]
	ds_read_b64_tr_b16 v[82:83], v0 offset:28672
	ds_read_b64_tr_b16 v[84:85], v0 offset:29184
	v_add_f32_e32 v98, v88, v102
	v_add_f32_e32 v98, v89, v98
	v_add_f32_e32 v98, v90, v98
	v_add_f32_e32 v146, v91, v98
	s_waitcnt lgkmcnt(6)
	v_mfma_f32_32x32x16_bf16 v[98:113], v[134:137], v[166:169], v[50:65]
	v_cvt_pk_bf16_f32 v160, v86, v87
	v_cvt_pk_bf16_f32 v161, v88, v89
	ds_read_b64_tr_b16 v[86:87], v0 offset:25600
	ds_read_b64_tr_b16 v[88:89], v0 offset:26112
	v_add_f32_e32 v134, v92, v146
	v_add_f32_e32 v134, v93, v134
	v_add_f32_e32 v134, v94, v134
	v_add_f32_e32 v134, v95, v134
	v_cvt_pk_bf16_f32 v154, v90, v91
	v_cvt_pk_bf16_f32 v155, v92, v93
	s_waitcnt lgkmcnt(7)
	v_mfma_f32_32x32x16_bf16 v[114:129], v[138:141], v[162:165], v[114:129]
	ds_read_b64_tr_b16 v[90:91], v0 offset:29696
	ds_read_b64_tr_b16 v[92:93], v0 offset:30208
	s_waitcnt lgkmcnt(8)
	v_mfma_f32_32x32x16_bf16 v[98:113], v[130:133], v[162:165], v[98:113]
	v_add_f32_e32 v130, v96, v134
	v_add_f32_e32 v130, v97, v130
	v_add_f32_e32 v130, v66, v130
	v_add_f32_e32 v130, v67, v130
	v_cvt_pk_bf16_f32 v156, v94, v95
	v_cvt_pk_bf16_f32 v157, v96, v97
	ds_read_b64_tr_b16 v[94:95], v0 offset:26624
	ds_read_b64_tr_b16 v[96:97], v0 offset:27136
	v_add_f32_e32 v130, v68, v130
	v_add_f32_e32 v130, v69, v130
	v_add_f32_e32 v130, v70, v130
	v_add_f32_e32 v130, v71, v130
	v_cvt_pk_bf16_f32 v150, v66, v67
	v_cvt_pk_bf16_f32 v151, v68, v69
	ds_read_b64_tr_b16 v[66:67], v0 offset:30720
	ds_read_b64_tr_b16 v[68:69], v0 offset:31232
	v_add_f32_e32 v130, v72, v130
	v_add_f32_e32 v130, v73, v130
	v_add_f32_e32 v130, v74, v130
	v_add_f32_e32 v130, v75, v130
	v_cvt_pk_bf16_f32 v152, v70, v71
	v_cvt_pk_bf16_f32 v153, v72, v73
	ds_read_b64_tr_b16 v[70:71], v0 offset:27648
	ds_read_b64_tr_b16 v[72:73], v0 offset:28160
	v_add_f32_e32 v130, v76, v130
	v_add_f32_e32 v130, v77, v130
	v_add_f32_e32 v130, v78, v130
	v_add_f32_e32 v130, v79, v130
	v_cvt_pk_bf16_f32 v146, v74, v75
	v_cvt_pk_bf16_f32 v147, v76, v77
	ds_read_b64_tr_b16 v[74:75], v0 offset:31744
	ds_read_b64_tr_b16 v[76:77], v0 offset:32256
	v_add_f32_e32 v0, v80, v130
	v_add_f32_e32 v0, v81, v0
	v_add_f32_e32 v0, 0, v0
	v_cvt_pk_bf16_f32 v148, v78, v79
	v_cvt_pk_bf16_f32 v149, v80, v81
	v_lshl_add_u64 v[78:79], v[144:145], 0, s[36:37]
	s_add_i32 s20, s86, s81
	s_mov_b32 s48, m0
	s_mov_b32 m0, s20
	s_nop 0
	global_load_lds_dwordx4 v[78:79], off
	s_mov_b32 m0, s48
	v_lshl_add_u64 v[78:79], v[142:143], 0, s[22:23]
	s_add_i32 s20, s85, s80
	s_mov_b32 s48, m0
	s_mov_b32 m0, s20
	s_nop 0
	global_load_lds_dwordx4 v[78:79], off
	s_mov_b32 m0, s48
	v_add_f32_e32 v0, v227, v0
	s_waitcnt lgkmcnt(14)
	v_mfma_f32_32x32x16_bf16 v[18:33], v[158:161], v[228:231], v[18:33]
	v_exp_f32_e32 v114, v114
	v_exp_f32_e32 v115, v115
	v_exp_f32_e32 v116, v116
	v_exp_f32_e32 v117, v117
	s_waitcnt lgkmcnt(12)
	v_mfma_f32_32x32x16_bf16 v[34:49], v[158:161], v[82:85], v[34:49]
	v_exp_f32_e32 v118, v118
	v_exp_f32_e32 v119, v119
	v_exp_f32_e32 v120, v120
	v_exp_f32_e32 v121, v121
	v_add_u32_e32 v82, s85, v214
	ds_read_b128 v[78:81], v82
	ds_read_b128 v[130:133], v82 offset:512
	s_waitcnt lgkmcnt(12)
	v_mfma_f32_32x32x16_bf16 v[18:33], v[154:157], v[86:89], v[18:33]
	v_exp_f32_e32 v122, v122
	v_exp_f32_e32 v123, v123
	v_exp_f32_e32 v124, v124
	v_exp_f32_e32 v125, v125
	ds_read_b128 v[134:137], v82 offset:2048
	ds_read_b128 v[138:141], v82 offset:2560
	s_waitcnt lgkmcnt(12)
	v_mfma_f32_32x32x16_bf16 v[34:49], v[154:157], v[90:93], v[34:49]
	v_exp_f32_e32 v126, v126
	v_exp_f32_e32 v127, v127
	v_exp_f32_e32 v128, v128
	v_exp_f32_e32 v129, v129
	s_waitcnt lgkmcnt(10)
	v_mfma_f32_32x32x16_bf16 v[18:33], v[150:153], v[94:97], v[18:33]
	v_exp_f32_e32 v98, v98
	v_exp_f32_e32 v99, v99
	v_exp_f32_e32 v100, v100
	v_exp_f32_e32 v101, v101
	s_waitcnt lgkmcnt(8)
	v_mfma_f32_32x32x16_bf16 v[34:49], v[150:153], v[66:69], v[34:49]
	v_exp_f32_e32 v102, v102
	v_exp_f32_e32 v103, v103
	v_exp_f32_e32 v104, v104
	v_exp_f32_e32 v105, v105
	s_waitcnt lgkmcnt(6)
	v_mfma_f32_32x32x16_bf16 v[18:33], v[146:149], v[70:73], v[18:33]
	v_exp_f32_e32 v106, v106
	v_exp_f32_e32 v107, v107
	v_exp_f32_e32 v108, v108
	v_exp_f32_e32 v109, v109
	s_waitcnt lgkmcnt(4)
	v_mfma_f32_32x32x16_bf16 v[34:49], v[146:149], v[74:77], v[34:49]
	v_exp_f32_e32 v110, v110
	v_exp_f32_e32 v111, v111
	v_exp_f32_e32 v112, v112
	v_exp_f32_e32 v113, v113
	s_add_i32 s20, s85, 0x2000
	s_cmpk_lg_i32 s85, 0x4000
	s_cselect_b32 s20, s20, 0
	v_add_u32_e32 v227, s86, v213
	s_waitcnt vmcnt(2) lgkmcnt(0)
	s_barrier
; #define WAIT_BAR(N) asm volatile("s_waitcnt vmcnt(" #N ") lgkmcnt(0)\n\ts_barrier":::"memory")
;   #define RESC() do{ if(!FIXREF&&resc){ asm volatile("s_waitcnt lgkmcnt(0)":::"memory"); \
;       _Pragma("unroll") for(int d_=0;d_<2;++d_) _Pragma("unroll") for(int r=0;r<16;++r)o[d_][r]*=wsf[crow(r,hi)]; } }while(0)
;   #define ROT() do{sl_prev=sl_cur;sl_cur=sl_next;sl_next=(sl_next==(NSLOT-1)*SLOTB)?0:sl_next+SLOTB;}while(0)
; template<int THRL,bool FIXREF,bool HALFK> __device__ __forceinline__ void attn_unit(float mref,long rowbase,int q0,const bf16*Qh,int PQ,const bf16*__restrict__ Kh_,int PK,const bf16*__restrict__ Vh_,int PV,bf16*Oh,int PO,const bf16*Gh,int PG,u32x4(&okeep)[4],int omode,float lam,float oml,const float ...
;     ...
;   for(;t+5<NT;t+=2){
;     STEP(pB0,pB1,pA0,pA1,t,true,true,true);     WAIT_BAR(2); RESC(); ROT();
;     STEP(pA0,pA1,pB0,pB1,t+1,true,true,true);   WAIT_BAR(2); RESC(); ROT();
;   }
	ds_read_b64_tr_b16 v[228:229], v227 offset:24576
	ds_read_b64_tr_b16 v[230:231], v227 offset:25088
	s_waitcnt lgkmcnt(5)
	v_mfma_f32_32x32x16_bf16 v[82:97], v[78:81], v[166:169], v[50:65]
	v_add_f32_e32 v66, v114, v115
	v_add_f32_e32 v66, v116, v66
	v_add_f32_e32 v66, v117, v66
	v_add_f32_e32 v66, v118, v66
	v_add_f32_e32 v66, v119, v66
	v_cvt_pk_bf16_f32 v158, v114, v115
	v_cvt_pk_bf16_f32 v159, v116, v117
	ds_read_b64_tr_b16 v[114:115], v227 offset:28672
	ds_read_b64_tr_b16 v[116:117], v227 offset:29184
	v_add_f32_e32 v66, v120, v66
	v_add_f32_e32 v66, v121, v66
	v_add_f32_e32 v66, v122, v66
	v_add_f32_e32 v146, v123, v66
	s_waitcnt lgkmcnt(6)
	v_mfma_f32_32x32x16_bf16 v[66:81], v[130:133], v[166:169], v[50:65]
	v_cvt_pk_bf16_f32 v160, v118, v119
	v_cvt_pk_bf16_f32 v161, v120, v121
	ds_read_b64_tr_b16 v[118:119], v227 offset:25600
	ds_read_b64_tr_b16 v[120:121], v227 offset:26112
	s_waitcnt lgkmcnt(7)
	v_mfma_f32_32x32x16_bf16 v[82:97], v[134:137], v[162:165], v[82:97]
	v_add_f32_e32 v130, v124, v146
	v_add_f32_e32 v130, v125, v130
	v_add_f32_e32 v130, v126, v130
	v_add_f32_e32 v130, v127, v130
	v_cvt_pk_bf16_f32 v154, v122, v123
	v_cvt_pk_bf16_f32 v155, v124, v125
	ds_read_b64_tr_b16 v[122:123], v227 offset:29696
	ds_read_b64_tr_b16 v[124:125], v227 offset:30208
	s_waitcnt lgkmcnt(8)
	v_mfma_f32_32x32x16_bf16 v[66:81], v[138:141], v[162:165], v[66:81]
	v_add_f32_e32 v130, v128, v130
	v_add_f32_e32 v130, v129, v130
	v_add_f32_e32 v130, v98, v130
	v_add_f32_e32 v130, v99, v130
	v_cvt_pk_bf16_f32 v156, v126, v127
	v_cvt_pk_bf16_f32 v157, v128, v129
	ds_read_b64_tr_b16 v[126:127], v227 offset:26624
	ds_read_b64_tr_b16 v[128:129], v227 offset:27136
	v_add_f32_e32 v130, v100, v130
	v_add_f32_e32 v130, v101, v130
	v_add_f32_e32 v130, v102, v130
	v_add_f32_e32 v130, v103, v130
	v_cvt_pk_bf16_f32 v150, v98, v99
	v_cvt_pk_bf16_f32 v151, v100, v101
	ds_read_b64_tr_b16 v[232:233], v227 offset:30720
	ds_read_b64_tr_b16 v[234:235], v227 offset:31232
	v_add_f32_e32 v98, v104, v130
	v_add_f32_e32 v98, v105, v98
	v_add_f32_e32 v98, v106, v98
	v_add_f32_e32 v98, v107, v98
	v_cvt_pk_bf16_f32 v152, v102, v103
	v_cvt_pk_bf16_f32 v153, v104, v105
	ds_read_b64_tr_b16 v[102:103], v227 offset:27648
	ds_read_b64_tr_b16 v[104:105], v227 offset:28160
	v_add_f32_e32 v98, v108, v98
	v_add_f32_e32 v98, v109, v98
	v_add_f32_e32 v98, v110, v98
	v_add_f32_e32 v98, v111, v98
	v_cvt_pk_bf16_f32 v146, v106, v107
	v_cvt_pk_bf16_f32 v147, v108, v109
	ds_read_b64_tr_b16 v[106:107], v227 offset:31744
	ds_read_b64_tr_b16 v[108:109], v227 offset:32256
	v_add_f32_e32 v98, v112, v98
	v_add_f32_e32 v98, v113, v98
	v_add_f32_e32 v98, 0, v98
	v_cvt_pk_bf16_f32 v148, v110, v111
	v_cvt_pk_bf16_f32 v149, v112, v113
	s_nop 0
	v_add_f32_e32 v227, v0, v98
	v_lshl_add_u64 v[98:99], v[144:145], 0, s[96:97]
	s_add_i32 s48, s85, s81
	s_mov_b32 s49, m0
	s_mov_b32 m0, s48
	s_nop 0
	global_load_lds_dwordx4 v[98:99], off
	s_mov_b32 m0, s49
	v_lshl_add_u64 v[142:143], v[142:143], 0, s[4:5]
	s_add_i32 s48, s20, s80
	s_mov_b32 s49, m0
	s_mov_b32 m0, s48
	s_nop 0
	global_load_lds_dwordx4 v[142:143], off
	s_mov_b32 m0, s49
	s_waitcnt lgkmcnt(14)
	v_mfma_f32_32x32x16_bf16 v[18:33], v[158:161], v[228:231], v[18:33]
	v_exp_f32_e32 v82, v82
	v_exp_f32_e32 v83, v83
	v_exp_f32_e32 v84, v84
	v_exp_f32_e32 v85, v85
	s_waitcnt lgkmcnt(12)
	v_mfma_f32_32x32x16_bf16 v[34:49], v[158:161], v[114:117], v[34:49]
	v_exp_f32_e32 v86, v86
	v_exp_f32_e32 v87, v87
	v_exp_f32_e32 v88, v88
	v_exp_f32_e32 v89, v89
	v_add_u32_e32 v0, s20, v214
	ds_read_b128 v[98:101], v0
	ds_read_b128 v[134:137], v0 offset:512
	s_waitcnt lgkmcnt(12)
	v_mfma_f32_32x32x16_bf16 v[18:33], v[154:157], v[118:121], v[18:33]
	v_exp_f32_e32 v90, v90
	v_exp_f32_e32 v91, v91
	v_exp_f32_e32 v92, v92
	v_exp_f32_e32 v93, v93
	ds_read_b128 v[138:141], v0 offset:2048
	ds_read_b128 v[130:133], v0 offset:2560
	s_waitcnt lgkmcnt(12)
	v_mfma_f32_32x32x16_bf16 v[34:49], v[154:157], v[122:125], v[34:49]
	v_exp_f32_e32 v94, v94
	v_exp_f32_e32 v95, v95
	v_exp_f32_e32 v96, v96
	v_exp_f32_e32 v97, v97
	s_waitcnt lgkmcnt(10)
	v_mfma_f32_32x32x16_bf16 v[18:33], v[150:153], v[126:129], v[18:33]
	v_exp_f32_e32 v66, v66
	v_exp_f32_e32 v67, v67
	v_exp_f32_e32 v68, v68
	v_exp_f32_e32 v69, v69
	s_waitcnt lgkmcnt(8)
	v_mfma_f32_32x32x16_bf16 v[34:49], v[150:153], v[232:235], v[34:49]
	v_exp_f32_e32 v70, v70
	v_exp_f32_e32 v71, v71
	v_exp_f32_e32 v72, v72
	v_exp_f32_e32 v73, v73
	s_waitcnt lgkmcnt(6)
	v_mfma_f32_32x32x16_bf16 v[18:33], v[146:149], v[102:105], v[18:33]
	v_exp_f32_e32 v74, v74
	v_exp_f32_e32 v75, v75
	v_exp_f32_e32 v76, v76
	v_exp_f32_e32 v77, v77
	s_waitcnt lgkmcnt(4)
	v_mfma_f32_32x32x16_bf16 v[34:49], v[146:149], v[106:109], v[34:49]
	v_exp_f32_e32 v78, v78
	v_exp_f32_e32 v79, v79
	v_exp_f32_e32 v80, v80
	v_exp_f32_e32 v81, v81
	s_add_i32 s48, s20, 0x2000
	s_cmpk_lg_i32 s20, 0x4000
	s_mov_b32 s87, s85
	s_cselect_b32 s85, s48, 0
	s_add_i32 s84, s84, 2
	v_lshl_add_u64 v[144:145], v[144:145], 0, s[92:93]
	s_mov_b32 s86, s20
	s_cmp_gt_u32 s84, 56
	s_waitcnt vmcnt(2) lgkmcnt(0)
	s_barrier
	s_cbranch_scc0 .LBB0_461
;   #define RESC() do{ if(!FIXREF&&resc){ asm volatile("s_waitcnt lgkmcnt(0)":::"memory"); \
;       _Pragma("unroll") for(int d_=0;d_<2;++d_) _Pragma("unroll") for(int r=0;r<16;++r)o[d_][r]*=wsf[crow(r,hi)]; } }while(0)
;   #define ROT() do{sl_prev=sl_cur;sl_cur=sl_next;sl_next=(sl_next==(NSLOT-1)*SLOTB)?0:sl_next+SLOTB;}while(0)
;   #define ENDW(tt) do{ if((tt)+3<NT){WAIT_BAR(2);} else if((tt)+2<NT){WAIT_BAR(1);} else {WAIT_BAR(0);} }while(0)
; template<int THRL,bool FIXREF,bool HALFK> __device__ __forceinline__ void attn_unit(float mref,long rowbase,int q0,const bf16*Qh,int PQ,const bf16*__restrict__ Kh_,int PK,const bf16*__restrict__ Vh_,int PV,bf16*Oh,int PO,const bf16*Gh,int PG,u32x4(&okeep)[4],int omode,float lam,float oml,const float ...
;     ...
;   for(;t+1<NT;t+=2){
;     STEP(pB0,pB1,pA0,pA1,t,(t+3<NT),(t+1<NT),(t+1<NT));       ENDW(t);   RESC(); ROT();
;     STEP(pA0,pA1,pB0,pB1,t+1,(t+4<NT),(t+2<NT),(t+2<NT));     ENDW(t+1); RESC(); ROT();
	s_and_b32 s20, s83, 0x3fffffc0
	s_lshl_b32 s20, s20, 2
	s_add_i32 s20, s20, 0
	s_cmp_lg_u32 0, -1
	s_cselect_b32 s50, 0, 0
	s_add_i32 s48, s50, 0x6000
	v_add_u32_e32 v0, s48, v216
	v_add3_u32 v0, v0, v215, v217
	ds_read_b64_tr_b16 v[142:143], v213 offset:32768
	ds_read_b64_tr_b16 v[144:145], v213 offset:33280
	v_add_f32_e32 v102, v82, v83
	v_add_f32_e32 v102, v84, v102
	v_add_f32_e32 v102, v85, v102
	v_add_f32_e32 v102, v86, v102
	v_add_f32_e32 v102, v87, v102
	v_cvt_pk_bf16_f32 v158, v82, v83
	v_cvt_pk_bf16_f32 v159, v84, v85
	s_waitcnt lgkmcnt(5)
	v_mfma_f32_32x32x16_bf16 v[114:129], v[98:101], v[166:169], v[50:65]
	ds_read_b64_tr_b16 v[82:83], v213 offset:36864
	ds_read_b64_tr_b16 v[84:85], v213 offset:37376
	v_add_f32_e32 v98, v88, v102
	v_add_f32_e32 v98, v89, v98
	v_add_f32_e32 v98, v90, v98
	v_add_f32_e32 v146, v91, v98
	v_cvt_pk_bf16_f32 v160, v86, v87
	v_cvt_pk_bf16_f32 v161, v88, v89
	s_waitcnt lgkmcnt(6)
	v_mfma_f32_32x32x16_bf16 v[98:113], v[134:137], v[166:169], v[50:65]
	ds_read_b64_tr_b16 v[86:87], v213 offset:33792
	ds_read_b64_tr_b16 v[88:89], v213 offset:34304
	v_add_f32_e32 v134, v92, v146
	v_add_f32_e32 v134, v93, v134
	v_add_f32_e32 v134, v94, v134
	v_add_f32_e32 v134, v95, v134
	v_cvt_pk_bf16_f32 v154, v90, v91
	v_cvt_pk_bf16_f32 v155, v92, v93
	s_waitcnt lgkmcnt(7)
	v_mfma_f32_32x32x16_bf16 v[114:129], v[138:141], v[162:165], v[114:129]
	ds_read_b64_tr_b16 v[90:91], v213 offset:37888
	ds_read_b64_tr_b16 v[92:93], v213 offset:38400
	s_waitcnt lgkmcnt(8)
	v_mfma_f32_32x32x16_bf16 v[98:113], v[130:133], v[162:165], v[98:113]
	v_add_f32_e32 v130, v96, v134
	v_add_f32_e32 v130, v97, v130
	v_add_f32_e32 v130, v66, v130
	v_add_f32_e32 v130, v67, v130
	v_cvt_pk_bf16_f32 v156, v94, v95
	v_cvt_pk_bf16_f32 v157, v96, v97
	ds_read_b64_tr_b16 v[94:95], v213 offset:34816
	ds_read_b64_tr_b16 v[96:97], v213 offset:35328
	v_add_f32_e32 v130, v68, v130
	v_add_f32_e32 v130, v69, v130
	v_add_f32_e32 v130, v70, v130
	v_add_f32_e32 v130, v71, v130
	v_cvt_pk_bf16_f32 v150, v66, v67
	v_cvt_pk_bf16_f32 v151, v68, v69
	ds_read_b64_tr_b16 v[66:67], v213 offset:38912
	ds_read_b64_tr_b16 v[68:69], v213 offset:39424
	v_add_f32_e32 v130, v72, v130
	v_add_f32_e32 v130, v73, v130
	v_add_f32_e32 v130, v74, v130
	v_add_f32_e32 v130, v75, v130
	v_cvt_pk_bf16_f32 v152, v70, v71
	v_cvt_pk_bf16_f32 v153, v72, v73
	ds_read_b64_tr_b16 v[70:71], v213 offset:35840
	ds_read_b64_tr_b16 v[72:73], v213 offset:36352
	v_add_f32_e32 v130, v76, v130
	v_add_f32_e32 v130, v77, v130
	v_add_f32_e32 v130, v78, v130
	v_add_f32_e32 v130, v79, v130
	v_cvt_pk_bf16_f32 v146, v74, v75
	v_cvt_pk_bf16_f32 v147, v76, v77
	ds_read_b64_tr_b16 v[74:75], v213 offset:39936
	ds_read_b64_tr_b16 v[76:77], v213 offset:40448
	v_add_f32_e32 v130, v80, v130
	v_add_f32_e32 v130, v81, v130
	v_add_f32_e32 v130, 0, v130
	v_cvt_pk_bf16_f32 v148, v78, v79
	v_cvt_pk_bf16_f32 v149, v80, v81
	s_mov_b64 s[48:49], 0x1f0000
	v_lshl_add_u64 v[78:79], v[174:175], 0, s[48:49]
	s_add_i32 s48, s50, s82
	s_add_i32 s49, s48, 0x4000
	s_mov_b32 s50, m0
	s_mov_b32 m0, s49
	s_nop 0
	global_load_lds_dwordx4 v[78:79], off
	s_mov_b32 m0, s50
	v_lshl_add_u64 v[78:79], v[172:173], 0, s[18:19]
	s_mov_b32 s49, m0
	s_mov_b32 m0, s80
	s_nop 0
	global_load_lds_dwordx4 v[78:79], off
	s_mov_b32 m0, s49
	v_add_f32_e32 v215, v227, v130
	s_waitcnt lgkmcnt(14)
	v_mfma_f32_32x32x16_bf16 v[18:33], v[158:161], v[142:145], v[18:33]
	v_exp_f32_e32 v114, v114
	v_exp_f32_e32 v115, v115
	v_exp_f32_e32 v116, v116
	v_exp_f32_e32 v117, v117
	s_waitcnt lgkmcnt(12)
	v_mfma_f32_32x32x16_bf16 v[34:49], v[158:161], v[82:85], v[34:49]
	v_exp_f32_e32 v118, v118
	v_exp_f32_e32 v119, v119
	v_exp_f32_e32 v120, v120
	v_exp_f32_e32 v121, v121
	ds_read_b128 v[78:81], v214
	ds_read_b128 v[82:85], v214 offset:512
	s_waitcnt lgkmcnt(12)
	v_mfma_f32_32x32x16_bf16 v[18:33], v[154:157], v[86:89], v[18:33]
	v_exp_f32_e32 v122, v122
	v_exp_f32_e32 v123, v123
	v_exp_f32_e32 v124, v124
	v_exp_f32_e32 v125, v125
	ds_read_b128 v[86:89], v214 offset:2048
	ds_read_b128 v[228:231], v214 offset:2560
	s_waitcnt lgkmcnt(12)
	v_mfma_f32_32x32x16_bf16 v[34:49], v[154:157], v[90:93], v[34:49]
	v_exp_f32_e32 v126, v126
	v_exp_f32_e32 v127, v127
	v_exp_f32_e32 v128, v128
	v_exp_f32_e32 v129, v129
	s_waitcnt lgkmcnt(10)
	v_mfma_f32_32x32x16_bf16 v[18:33], v[150:153], v[94:97], v[18:33]
	v_exp_f32_e32 v98, v98
	v_exp_f32_e32 v99, v99
	v_exp_f32_e32 v100, v100
	v_exp_f32_e32 v101, v101
	s_waitcnt lgkmcnt(8)
	v_mfma_f32_32x32x16_bf16 v[34:49], v[150:153], v[66:69], v[34:49]
	v_exp_f32_e32 v102, v102
	v_exp_f32_e32 v103, v103
	v_exp_f32_e32 v104, v104
	v_exp_f32_e32 v105, v105
	s_waitcnt lgkmcnt(6)
	v_mfma_f32_32x32x16_bf16 v[18:33], v[146:149], v[70:73], v[18:33]
	v_exp_f32_e32 v106, v106
	v_exp_f32_e32 v107, v107
	v_exp_f32_e32 v108, v108
	v_exp_f32_e32 v109, v109
	s_waitcnt lgkmcnt(4)
	v_mfma_f32_32x32x16_bf16 v[34:49], v[146:149], v[74:77], v[34:49]
	v_exp_f32_e32 v110, v110
	v_exp_f32_e32 v111, v111
	v_exp_f32_e32 v112, v112
	v_exp_f32_e32 v113, v113
	s_waitcnt vmcnt(2) lgkmcnt(0)
	s_barrier
;   #define RESC() do{ if(!FIXREF&&resc){ asm volatile("s_waitcnt lgkmcnt(0)":::"memory"); \
;       _Pragma("unroll") for(int d_=0;d_<2;++d_) _Pragma("unroll") for(int r=0;r<16;++r)o[d_][r]*=wsf[crow(r,hi)]; } }while(0)
;   #define ROT() do{sl_prev=sl_cur;sl_cur=sl_next;sl_next=(sl_next==(NSLOT-1)*SLOTB)?0:sl_next+SLOTB;}while(0)
;   #define ENDW(tt) do{ if((tt)+3<NT){WAIT_BAR(2);} else if((tt)+2<NT){WAIT_BAR(1);} else {WAIT_BAR(0);} }while(0)
; template<int THRL,bool FIXREF,bool HALFK> __device__ __forceinline__ void attn_unit(float mref,long rowbase,int q0,const bf16*Qh,int PQ,const bf16*__restrict__ Kh_,int PK,const bf16*__restrict__ Vh_,int PV,bf16*Oh,int PO,const bf16*Gh,int PG,u32x4(&okeep)[4],int omode,float lam,float oml,const float ...
;     ...
;   for(;t+1<NT;t+=2){
;     STEP(pB0,pB1,pA0,pA1,t,(t+3<NT),(t+1<NT),(t+1<NT));       ENDW(t);   RESC(); ROT();
;     STEP(pA0,pA1,pB0,pB1,t+1,(t+4<NT),(t+2<NT),(t+2<NT));     ENDW(t+1); RESC(); ROT();
	ds_read_b64_tr_b16 v[90:91], v213 offset:40960
	ds_read_b64_tr_b16 v[92:93], v213 offset:41472
	v_add_f32_e32 v66, v114, v115
	v_add_f32_e32 v66, v116, v66
	v_add_f32_e32 v66, v117, v66
	v_add_f32_e32 v66, v118, v66
	v_add_f32_e32 v66, v119, v66
	v_cvt_pk_bf16_f32 v158, v114, v115
	v_cvt_pk_bf16_f32 v159, v116, v117
	s_waitcnt lgkmcnt(5)
	v_mfma_f32_32x32x16_bf16 v[130:145], v[78:81], v[166:169], v[50:65]
	ds_read_b64_tr_b16 v[94:95], v213 offset:45056
	ds_read_b64_tr_b16 v[96:97], v213 offset:45568
	v_add_f32_e32 v66, v120, v66
	v_add_f32_e32 v66, v121, v66
	v_add_f32_e32 v66, v122, v66
	v_add_f32_e32 v114, v123, v66
	s_waitcnt lgkmcnt(6)
	v_mfma_f32_32x32x16_bf16 v[66:81], v[82:85], v[166:169], v[50:65]
	v_cvt_pk_bf16_f32 v160, v118, v119
	v_cvt_pk_bf16_f32 v161, v120, v121
	ds_read_b64_tr_b16 v[82:83], v213 offset:41984
	ds_read_b64_tr_b16 v[84:85], v213 offset:42496
	s_waitcnt lgkmcnt(7)
	v_mfma_f32_32x32x16_bf16 v[130:145], v[86:89], v[162:165], v[130:145]
	v_add_f32_e32 v86, v124, v114
	v_add_f32_e32 v86, v125, v86
	v_add_f32_e32 v86, v126, v86
	v_add_f32_e32 v114, v127, v86
	v_cvt_pk_bf16_f32 v154, v122, v123
	v_cvt_pk_bf16_f32 v155, v124, v125
	ds_read_b64_tr_b16 v[86:87], v213 offset:46080
	ds_read_b64_tr_b16 v[88:89], v213 offset:46592
	s_waitcnt lgkmcnt(8)
	v_mfma_f32_32x32x16_bf16 v[66:81], v[228:231], v[162:165], v[66:81]
	v_add_f32_e32 v114, v128, v114
	v_add_f32_e32 v114, v129, v114
	v_add_f32_e32 v114, v98, v114
	v_add_f32_e32 v118, v99, v114
	v_cvt_pk_bf16_f32 v156, v126, v127
	v_cvt_pk_bf16_f32 v157, v128, v129
	ds_read_b64_tr_b16 v[114:115], v213 offset:43008
	ds_read_b64_tr_b16 v[116:117], v213 offset:43520
	v_add_f32_e32 v118, v100, v118
	v_add_f32_e32 v118, v101, v118
	v_add_f32_e32 v118, v102, v118
	v_add_f32_e32 v118, v103, v118
	v_cvt_pk_bf16_f32 v150, v98, v99
	v_cvt_pk_bf16_f32 v151, v100, v101
	ds_read_b64_tr_b16 v[98:99], v213 offset:47104
	ds_read_b64_tr_b16 v[100:101], v213 offset:47616
	v_add_f32_e32 v118, v104, v118
	v_add_f32_e32 v118, v105, v118
	v_add_f32_e32 v118, v106, v118
	v_add_f32_e32 v118, v107, v118
	v_cvt_pk_bf16_f32 v152, v102, v103
	v_cvt_pk_bf16_f32 v153, v104, v105
	ds_read_b64_tr_b16 v[102:103], v213 offset:44032
	ds_read_b64_tr_b16 v[104:105], v213 offset:44544
	v_add_f32_e32 v118, v108, v118
	v_add_f32_e32 v118, v109, v118
	v_add_f32_e32 v118, v110, v118
	v_add_f32_e32 v118, v111, v118
	v_cvt_pk_bf16_f32 v146, v106, v107
	v_cvt_pk_bf16_f32 v147, v108, v109
	ds_read_b64_tr_b16 v[106:107], v213 offset:48128
	ds_read_b64_tr_b16 v[108:109], v213 offset:48640
	v_add_f32_e32 v118, v112, v118
	v_add_f32_e32 v118, v113, v118
	v_add_f32_e32 v118, 0, v118
	v_cvt_pk_bf16_f32 v148, v110, v111
	v_cvt_pk_bf16_f32 v149, v112, v113
	s_mov_b64 s[50:51], 0x1f8000
	v_lshl_add_u64 v[110:111], v[174:175], 0, s[50:51]
	s_mov_b32 s49, m0
	s_mov_b32 m0, s81
	s_nop 0
	global_load_lds_dwordx4 v[110:111], off
	s_mov_b32 m0, s49
	v_lshl_add_u64 v[110:111], v[172:173], 0, s[6:7]
	s_add_i32 s49, s48, 0x8000
	s_mov_b32 s50, m0
	s_mov_b32 m0, s49
	s_nop 0
	global_load_lds_dwordx4 v[110:111], off
	s_mov_b32 m0, s50
	v_add_f32_e32 v215, v215, v118
	s_waitcnt lgkmcnt(14)
	v_mfma_f32_32x32x16_bf16 v[18:33], v[158:161], v[90:93], v[18:33]
	v_exp_f32_e32 v130, v130
	v_exp_f32_e32 v131, v131
	v_exp_f32_e32 v132, v132
	v_exp_f32_e32 v133, v133
	s_waitcnt lgkmcnt(12)
	v_mfma_f32_32x32x16_bf16 v[34:49], v[158:161], v[94:97], v[34:49]
	v_exp_f32_e32 v134, v134
	v_exp_f32_e32 v135, v135
	v_exp_f32_e32 v136, v136
	v_exp_f32_e32 v137, v137
	ds_read_b128 v[90:93], v214 offset:8192
	ds_read_b128 v[110:113], v214 offset:8704
	s_waitcnt lgkmcnt(12)
	v_mfma_f32_32x32x16_bf16 v[18:33], v[154:157], v[82:85], v[18:33]
	v_exp_f32_e32 v138, v138
	v_exp_f32_e32 v139, v139
	v_exp_f32_e32 v140, v140
	v_exp_f32_e32 v141, v141
	ds_read_b128 v[228:231], v214 offset:10240
	ds_read_b128 v[232:235], v214 offset:10752
	s_waitcnt lgkmcnt(12)
	v_mfma_f32_32x32x16_bf16 v[34:49], v[154:157], v[86:89], v[34:49]
	v_exp_f32_e32 v142, v142
	v_exp_f32_e32 v143, v143
	v_exp_f32_e32 v144, v144
	v_exp_f32_e32 v145, v145
	s_waitcnt lgkmcnt(10)
	v_mfma_f32_32x32x16_bf16 v[18:33], v[150:153], v[114:117], v[18:33]
	v_exp_f32_e32 v66, v66
	v_exp_f32_e32 v67, v67
	v_exp_f32_e32 v68, v68
	v_exp_f32_e32 v69, v69
	s_waitcnt lgkmcnt(8)
	v_mfma_f32_32x32x16_bf16 v[34:49], v[150:153], v[98:101], v[34:49]
	v_exp_f32_e32 v70, v70
	v_exp_f32_e32 v71, v71
	v_exp_f32_e32 v72, v72
	v_exp_f32_e32 v73, v73
	s_waitcnt lgkmcnt(6)
	v_mfma_f32_32x32x16_bf16 v[18:33], v[146:149], v[102:105], v[18:33]
	v_exp_f32_e32 v74, v74
	v_exp_f32_e32 v75, v75
	v_exp_f32_e32 v76, v76
	v_exp_f32_e32 v77, v77
	s_waitcnt lgkmcnt(4)
	v_mfma_f32_32x32x16_bf16 v[34:49], v[146:149], v[106:109], v[34:49]
	v_exp_f32_e32 v78, v78
	v_exp_f32_e32 v79, v79
	v_exp_f32_e32 v80, v80
	v_exp_f32_e32 v81, v81
	s_waitcnt vmcnt(2) lgkmcnt(0)
	s_barrier
;   #define RESC() do{ if(!FIXREF&&resc){ asm volatile("s_waitcnt lgkmcnt(0)":::"memory"); \
;       _Pragma("unroll") for(int d_=0;d_<2;++d_) _Pragma("unroll") for(int r=0;r<16;++r)o[d_][r]*=wsf[crow(r,hi)]; } }while(0)
;   #define ROT() do{sl_prev=sl_cur;sl_cur=sl_next;sl_next=(sl_next==(NSLOT-1)*SLOTB)?0:sl_next+SLOTB;}while(0)
;   #define ENDW(tt) do{ if((tt)+3<NT){WAIT_BAR(2);} else if((tt)+2<NT){WAIT_BAR(1);} else {WAIT_BAR(0);} }while(0)
; template<int THRL,bool FIXREF,bool HALFK> __device__ __forceinline__ void attn_unit(float mref,long rowbase,int q0,const bf16*Qh,int PQ,const bf16*__restrict__ Kh_,int PK,const bf16*__restrict__ Vh_,int PV,bf16*Oh,int PO,const bf16*Gh,int PG,u32x4(&okeep)[4],int omode,float lam,float oml,const float ...
;     ...
;   for(;t+1<NT;t+=2){
;     STEP(pB0,pB1,pA0,pA1,t,(t+3<NT),(t+1<NT),(t+1<NT));       ENDW(t);   RESC(); ROT();
;     STEP(pA0,pA1,pB0,pB1,t+1,(t+4<NT),(t+2<NT),(t+2<NT));     ENDW(t+1); RESC(); ROT();
	ds_read_b64_tr_b16 v[98:99], v213 offset:24576
	ds_read_b64_tr_b16 v[100:101], v213 offset:25088
	v_add_f32_e32 v82, v130, v131
	v_add_f32_e32 v82, v132, v82
	v_add_f32_e32 v82, v133, v82
	v_add_f32_e32 v82, v134, v82
	v_add_f32_e32 v82, v135, v82
	v_cvt_pk_bf16_f32 v158, v130, v131
	v_cvt_pk_bf16_f32 v159, v132, v133
	s_waitcnt lgkmcnt(5)
	v_mfma_f32_32x32x16_bf16 v[114:129], v[90:93], v[166:169], v[50:65]
	ds_read_b64_tr_b16 v[102:103], v213 offset:28672
	ds_read_b64_tr_b16 v[104:105], v213 offset:29184
	v_add_f32_e32 v82, v136, v82
	v_add_f32_e32 v82, v137, v82
	v_add_f32_e32 v82, v138, v82
	v_add_f32_e32 v130, v139, v82
	v_cvt_pk_bf16_f32 v160, v134, v135
	v_cvt_pk_bf16_f32 v161, v136, v137
	s_waitcnt lgkmcnt(6)
	v_mfma_f32_32x32x16_bf16 v[82:97], v[110:113], v[166:169], v[50:65]
	ds_read_b64_tr_b16 v[106:107], v213 offset:25600
	ds_read_b64_tr_b16 v[108:109], v213 offset:26112
	v_add_f32_e32 v110, v140, v130
	v_add_f32_e32 v110, v141, v110
	v_add_f32_e32 v110, v142, v110
	v_add_f32_e32 v130, v143, v110
	v_cvt_pk_bf16_f32 v154, v138, v139
	v_cvt_pk_bf16_f32 v155, v140, v141
	s_waitcnt lgkmcnt(7)
	v_mfma_f32_32x32x16_bf16 v[114:129], v[228:231], v[162:165], v[114:129]
	ds_read_b64_tr_b16 v[110:111], v213 offset:29696
	ds_read_b64_tr_b16 v[112:113], v213 offset:30208
	v_add_f32_e32 v130, v144, v130
	v_add_f32_e32 v130, v145, v130
	v_add_f32_e32 v130, v66, v130
	v_add_f32_e32 v134, v67, v130
	v_cvt_pk_bf16_f32 v156, v142, v143
	v_cvt_pk_bf16_f32 v157, v144, v145
	s_waitcnt lgkmcnt(8)
	v_mfma_f32_32x32x16_bf16 v[82:97], v[232:235], v[162:165], v[82:97]
	ds_read_b64_tr_b16 v[130:131], v213 offset:26624
	ds_read_b64_tr_b16 v[132:133], v213 offset:27136
	v_add_f32_e32 v134, v68, v134
	v_add_f32_e32 v134, v69, v134
	v_add_f32_e32 v134, v70, v134
	v_add_f32_e32 v134, v71, v134
	v_cvt_pk_bf16_f32 v150, v66, v67
	v_cvt_pk_bf16_f32 v151, v68, v69
	ds_read_b64_tr_b16 v[66:67], v213 offset:30720
	ds_read_b64_tr_b16 v[68:69], v213 offset:31232
	v_add_f32_e32 v134, v72, v134
	v_add_f32_e32 v134, v73, v134
	v_add_f32_e32 v134, v74, v134
	v_add_f32_e32 v134, v75, v134
	v_cvt_pk_bf16_f32 v152, v70, v71
	v_cvt_pk_bf16_f32 v153, v72, v73
	ds_read_b64_tr_b16 v[70:71], v213 offset:27648
	ds_read_b64_tr_b16 v[72:73], v213 offset:28160
	v_add_f32_e32 v134, v76, v134
	v_add_f32_e32 v134, v77, v134
	v_add_f32_e32 v134, v78, v134
	v_add_f32_e32 v134, v79, v134
	v_cvt_pk_bf16_f32 v146, v74, v75
	v_cvt_pk_bf16_f32 v147, v76, v77
	ds_read_b64_tr_b16 v[74:75], v213 offset:31744
	ds_read_b64_tr_b16 v[76:77], v213 offset:32256
	v_add_f32_e32 v134, v80, v134
	v_add_f32_e32 v134, v81, v134
	v_add_f32_e32 v134, 0, v134
	v_cvt_pk_bf16_f32 v148, v78, v79
	v_cvt_pk_bf16_f32 v149, v80, v81
	v_lshl_add_u64 v[78:79], v[172:173], 0, s[94:95]
	s_add_i32 s48, s48, 0xa000
	s_mov_b32 s49, m0
	s_mov_b32 m0, s48
	s_nop 0
	global_load_lds_dwordx4 v[78:79], off
	s_mov_b32 m0, s49
	v_add_f32_e32 v174, v215, v134
	s_waitcnt lgkmcnt(14)
	v_mfma_f32_32x32x16_bf16 v[18:33], v[158:161], v[98:101], v[18:33]
	v_exp_f32_e32 v114, v114
	v_exp_f32_e32 v115, v115
	v_exp_f32_e32 v116, v116
	v_exp_f32_e32 v117, v117
	s_waitcnt lgkmcnt(12)
	v_mfma_f32_32x32x16_bf16 v[34:49], v[158:161], v[102:105], v[34:49]
	v_exp_f32_e32 v118, v118
	v_exp_f32_e32 v119, v119
	v_exp_f32_e32 v120, v120
	v_exp_f32_e32 v121, v121
	ds_read_b128 v[78:81], v214 offset:16384
	ds_read_b128 v[134:137], v214 offset:16896
	s_waitcnt lgkmcnt(12)
	v_mfma_f32_32x32x16_bf16 v[18:33], v[154:157], v[106:109], v[18:33]
	v_exp_f32_e32 v122, v122
	v_exp_f32_e32 v123, v123
	v_exp_f32_e32 v124, v124
	v_exp_f32_e32 v125, v125
	ds_read_b128 v[138:141], v214 offset:18432
	ds_read_b128 v[142:145], v214 offset:18944
	s_waitcnt lgkmcnt(12)
	v_mfma_f32_32x32x16_bf16 v[34:49], v[154:157], v[110:113], v[34:49]
	v_exp_f32_e32 v126, v126
	v_exp_f32_e32 v127, v127
	v_exp_f32_e32 v128, v128
	v_exp_f32_e32 v129, v129
	s_waitcnt lgkmcnt(10)
	v_mfma_f32_32x32x16_bf16 v[18:33], v[150:153], v[130:133], v[18:33]
	v_exp_f32_e32 v82, v82
	v_exp_f32_e32 v83, v83
	v_exp_f32_e32 v84, v84
	v_exp_f32_e32 v85, v85
	s_waitcnt lgkmcnt(8)
	v_mfma_f32_32x32x16_bf16 v[34:49], v[150:153], v[66:69], v[34:49]
	v_exp_f32_e32 v86, v86
	v_exp_f32_e32 v87, v87
	v_exp_f32_e32 v88, v88
	v_exp_f32_e32 v89, v89
	s_waitcnt lgkmcnt(6)
	v_mfma_f32_32x32x16_bf16 v[18:33], v[146:149], v[70:73], v[18:33]
	v_exp_f32_e32 v90, v90
	v_exp_f32_e32 v91, v91
	v_exp_f32_e32 v92, v92
	v_exp_f32_e32 v93, v93
	s_waitcnt lgkmcnt(4)
	v_mfma_f32_32x32x16_bf16 v[34:49], v[146:149], v[74:77], v[34:49]
	v_exp_f32_e32 v94, v94
	v_exp_f32_e32 v95, v95
	v_exp_f32_e32 v96, v96
	v_exp_f32_e32 v97, v97
	s_waitcnt vmcnt(1) lgkmcnt(0)
	s_barrier
;   #define RESC() do{ if(!FIXREF&&resc){ asm volatile("s_waitcnt lgkmcnt(0)":::"memory"); \
;       _Pragma("unroll") for(int d_=0;d_<2;++d_) _Pragma("unroll") for(int r=0;r<16;++r)o[d_][r]*=wsf[crow(r,hi)]; } }while(0)
;   #define ROT() do{sl_prev=sl_cur;sl_cur=sl_next;sl_next=(sl_next==(NSLOT-1)*SLOTB)?0:sl_next+SLOTB;}while(0)
;   #define ENDW(tt) do{ if((tt)+3<NT){WAIT_BAR(2);} else if((tt)+2<NT){WAIT_BAR(1);} else {WAIT_BAR(0);} }while(0)
; template<int THRL,bool FIXREF,bool HALFK> __device__ __forceinline__ void attn_unit(float mref,long rowbase,int q0,const bf16*Qh,int PQ,const bf16*__restrict__ Kh_,int PK,const bf16*__restrict__ Vh_,int PV,bf16*Oh,int PO,const bf16*Gh,int PG,u32x4(&okeep)[4],int omode,float lam,float oml,const float ...
;     ...
;   for(;t+1<NT;t+=2){
;     STEP(pB0,pB1,pA0,pA1,t,(t+3<NT),(t+1<NT),(t+1<NT));       ENDW(t);   RESC(); ROT();
;     STEP(pA0,pA1,pB0,pB1,t+1,(t+4<NT),(t+2<NT),(t+2<NT));     ENDW(t+1); RESC(); ROT();
	ds_read_b64_tr_b16 v[130:131], v213 offset:32768
	ds_read_b64_tr_b16 v[132:133], v213 offset:33280
	v_add_f32_e32 v66, v114, v115
	v_add_f32_e32 v66, v116, v66
	v_add_f32_e32 v66, v117, v66
	v_add_f32_e32 v66, v118, v66
	v_add_f32_e32 v66, v119, v66
	v_cvt_pk_bf16_f32 v158, v114, v115
	v_cvt_pk_bf16_f32 v159, v116, v117
	s_waitcnt lgkmcnt(5)
	v_mfma_f32_32x32x16_bf16 v[98:113], v[78:81], v[166:169], v[50:65]
	ds_read_b64_tr_b16 v[114:115], v213 offset:36864
	ds_read_b64_tr_b16 v[116:117], v213 offset:37376
	v_add_f32_e32 v66, v120, v66
	v_add_f32_e32 v66, v121, v66
	v_add_f32_e32 v66, v122, v66
	v_add_f32_e32 v146, v123, v66
	s_waitcnt lgkmcnt(6)
	v_mfma_f32_32x32x16_bf16 v[66:81], v[134:137], v[166:169], v[50:65]
	v_cvt_pk_bf16_f32 v160, v118, v119
	v_cvt_pk_bf16_f32 v161, v120, v121
	ds_read_b64_tr_b16 v[118:119], v213 offset:33792
	ds_read_b64_tr_b16 v[120:121], v213 offset:34304
	v_add_f32_e32 v134, v124, v146
	v_add_f32_e32 v134, v125, v134
	v_add_f32_e32 v134, v126, v134
	s_waitcnt lgkmcnt(7)
	v_mfma_f32_32x32x16_bf16 v[98:113], v[138:141], v[162:165], v[98:113]
	v_add_f32_e32 v138, v127, v134
	v_cvt_pk_bf16_f32 v154, v122, v123
	v_cvt_pk_bf16_f32 v155, v124, v125
	ds_read_b64_tr_b16 v[134:135], v213 offset:37888
	ds_read_b64_tr_b16 v[136:137], v213 offset:38400
	s_waitcnt lgkmcnt(8)
	v_mfma_f32_32x32x16_bf16 v[66:81], v[142:145], v[162:165], v[66:81]
	v_add_f32_e32 v122, v128, v138
	v_add_f32_e32 v122, v129, v122
	v_add_f32_e32 v122, v82, v122
	v_add_f32_e32 v122, v83, v122
	v_cvt_pk_bf16_f32 v156, v126, v127
	v_cvt_pk_bf16_f32 v157, v128, v129
	ds_read_b64_tr_b16 v[124:125], v213 offset:34816
	ds_read_b64_tr_b16 v[126:127], v213 offset:35328
	v_add_f32_e32 v122, v84, v122
	v_add_f32_e32 v122, v85, v122
	v_add_f32_e32 v122, v86, v122
	v_add_f32_e32 v122, v87, v122
	v_cvt_pk_bf16_f32 v150, v82, v83
	v_cvt_pk_bf16_f32 v151, v84, v85
	ds_read_b64_tr_b16 v[82:83], v213 offset:38912
	ds_read_b64_tr_b16 v[84:85], v213 offset:39424
	v_add_f32_e32 v122, v88, v122
	v_add_f32_e32 v122, v89, v122
	v_add_f32_e32 v122, v90, v122
	v_add_f32_e32 v122, v91, v122
	v_cvt_pk_bf16_f32 v152, v86, v87
	v_cvt_pk_bf16_f32 v153, v88, v89
	ds_read_b64_tr_b16 v[86:87], v213 offset:35840
	ds_read_b64_tr_b16 v[88:89], v213 offset:36352
	v_add_f32_e32 v122, v92, v122
	v_add_f32_e32 v122, v93, v122
	v_add_f32_e32 v122, v94, v122
	v_add_f32_e32 v122, v95, v122
	v_cvt_pk_bf16_f32 v146, v90, v91
	v_cvt_pk_bf16_f32 v147, v92, v93
	ds_read_b64_tr_b16 v[90:91], v213 offset:39936
	ds_read_b64_tr_b16 v[92:93], v213 offset:40448
	v_add_f32_e32 v122, v96, v122
	v_add_f32_e32 v122, v97, v122
	v_add_f32_e32 v122, 0, v122
	v_cvt_pk_bf16_f32 v148, v94, v95
	v_cvt_pk_bf16_f32 v149, v96, v97
	v_lshl_add_u64 v[94:95], v[172:173], 0, s[26:27]
	s_mov_b32 s48, m0
	s_mov_b32 m0, s80
	s_nop 0
	global_load_lds_dwordx4 v[94:95], off
	s_mov_b32 m0, s48
	v_add_f32_e32 v122, v174, v122
	s_waitcnt lgkmcnt(14)
	v_mfma_f32_32x32x16_bf16 v[18:33], v[158:161], v[130:133], v[18:33]
	v_exp_f32_e32 v98, v98
	v_exp_f32_e32 v99, v99
	v_exp_f32_e32 v100, v100
	v_exp_f32_e32 v101, v101
	s_waitcnt lgkmcnt(12)
	v_mfma_f32_32x32x16_bf16 v[34:49], v[158:161], v[114:117], v[34:49]
	v_exp_f32_e32 v102, v102
	v_exp_f32_e32 v103, v103
	v_exp_f32_e32 v104, v104
	v_exp_f32_e32 v105, v105
	ds_read_b128 v[128:131], v214
	ds_read_b128 v[138:141], v214 offset:512
	s_waitcnt lgkmcnt(12)
	v_mfma_f32_32x32x16_bf16 v[18:33], v[154:157], v[118:121], v[18:33]
	v_exp_f32_e32 v106, v106
	v_exp_f32_e32 v107, v107
	v_exp_f32_e32 v108, v108
	v_exp_f32_e32 v109, v109
	ds_read_b128 v[142:145], v214 offset:2048
	ds_read_b128 v[172:175], v214 offset:2560
	s_waitcnt lgkmcnt(12)
	v_mfma_f32_32x32x16_bf16 v[34:49], v[154:157], v[134:137], v[34:49]
	v_exp_f32_e32 v110, v110
	v_exp_f32_e32 v111, v111
	v_exp_f32_e32 v112, v112
	v_exp_f32_e32 v113, v113
	s_waitcnt lgkmcnt(10)
	v_mfma_f32_32x32x16_bf16 v[18:33], v[150:153], v[124:127], v[18:33]
	v_exp_f32_e32 v66, v66
	v_exp_f32_e32 v67, v67
	v_exp_f32_e32 v68, v68
	v_exp_f32_e32 v69, v69
	s_waitcnt lgkmcnt(8)
	v_mfma_f32_32x32x16_bf16 v[34:49], v[150:153], v[82:85], v[34:49]
	v_exp_f32_e32 v70, v70
	v_exp_f32_e32 v71, v71
	v_exp_f32_e32 v72, v72
	v_exp_f32_e32 v73, v73
	s_waitcnt lgkmcnt(6)
	v_mfma_f32_32x32x16_bf16 v[18:33], v[146:149], v[86:89], v[18:33]
	v_exp_f32_e32 v74, v74
	v_exp_f32_e32 v75, v75
	v_exp_f32_e32 v76, v76
	v_exp_f32_e32 v77, v77
	s_waitcnt lgkmcnt(4)
	v_mfma_f32_32x32x16_bf16 v[34:49], v[146:149], v[90:93], v[34:49]
	v_exp_f32_e32 v78, v78
	v_exp_f32_e32 v79, v79
	v_exp_f32_e32 v80, v80
	v_exp_f32_e32 v81, v81
	s_waitcnt vmcnt(0) lgkmcnt(0)
	s_barrier
;   #define RESC() do{ if(!FIXREF&&resc){ asm volatile("s_waitcnt lgkmcnt(0)":::"memory"); \
;       _Pragma("unroll") for(int d_=0;d_<2;++d_) _Pragma("unroll") for(int r=0;r<16;++r)o[d_][r]*=wsf[crow(r,hi)]; } }while(0)
;   #define PKW(P,B) cvtpk_s(P[B],P[B+1])
; template<int THRL,bool FIXREF,bool HALFK> __device__ __forceinline__ void attn_unit(float mref,long rowbase,int q0,const bf16*Qh,int PQ,const bf16*__restrict__ Kh_,int PK,const bf16*__restrict__ Vh_,int PV,bf16*Oh,int PO,const bf16*Gh,int PG,u32x4(&okeep)[4],int omode,float lam,float oml,const float ...
;     ...
;   STEP(pB0,pB1,pA0,pA1,NT-1,false,false,false); RESC();
;   { float sacc=pB0[0]+pB0[1]; _Pragma("unroll") for(int r=2;r<16;++r)sacc+=pB0[r]; _Pragma("unroll") for(int r=0;r<16;++r)sacc+=pB1[r]; l_reg+=sacc;
;     pw0=(u32x4){PKW(pB0,0),PKW(pB0,2),PKW(pB0,4),PKW(pB0,6)};pw1=(u32x4){PKW(pB0,8),PKW(pB0,10),PKW(pB0,12),PKW(pB0,14)};pw2=(u32x4){PKW(pB1,0),PKW(pB1,2),PKW(pB1,4),PKW(pB1,6)};pw3=(u32x4){PKW(pB1,8),PKW(pB1,10),PKW(pB1,12),PKW(pB1,14)};
	ds_read_b64_tr_b16 v[114:115], v213 offset:40960
	ds_read_b64_tr_b16 v[116:117], v213 offset:41472
	v_add_f32_e32 v82, v98, v99
	v_add_f32_e32 v82, v100, v82
	v_add_f32_e32 v82, v101, v82
	v_add_f32_e32 v82, v102, v82
	v_add_f32_e32 v118, v103, v82
	v_cvt_pk_bf16_f32 v158, v98, v99
	v_cvt_pk_bf16_f32 v159, v100, v101
	s_waitcnt lgkmcnt(5)
	v_mfma_f32_32x32x16_bf16 v[82:97], v[128:131], v[166:169], v[50:65]
	ds_read_b64_tr_b16 v[98:99], v213 offset:45056
	ds_read_b64_tr_b16 v[100:101], v213 offset:45568
	v_add_f32_e32 v118, v104, v118
	v_add_f32_e32 v118, v105, v118
	v_add_f32_e32 v118, v106, v118
	v_add_f32_e32 v123, v107, v118
	v_cvt_pk_bf16_f32 v160, v102, v103
	v_cvt_pk_bf16_f32 v161, v104, v105
	s_waitcnt lgkmcnt(6)
	v_mfma_f32_32x32x16_bf16 v[50:65], v[138:141], v[166:169], v[50:65]
	ds_read_b64_tr_b16 v[118:119], v213 offset:41984
	ds_read_b64_tr_b16 v[120:121], v213 offset:42496
	v_add_f32_e32 v102, v108, v123
	v_add_f32_e32 v102, v109, v102
	v_add_f32_e32 v102, v110, v102
	v_add_f32_e32 v123, v111, v102
	v_cvt_pk_bf16_f32 v154, v106, v107
	v_cvt_pk_bf16_f32 v155, v108, v109
	s_waitcnt lgkmcnt(7)
	v_mfma_f32_32x32x16_bf16 v[82:97], v[142:145], v[162:165], v[82:97]
	ds_read_b64_tr_b16 v[102:103], v213 offset:46080
	ds_read_b64_tr_b16 v[104:105], v213 offset:46592
	v_add_f32_e32 v106, v112, v123
	v_add_f32_e32 v106, v113, v106
	v_add_f32_e32 v106, v66, v106
	v_add_f32_e32 v123, v67, v106
	v_cvt_pk_bf16_f32 v156, v110, v111
	v_cvt_pk_bf16_f32 v157, v112, v113
	s_waitcnt lgkmcnt(8)
	v_mfma_f32_32x32x16_bf16 v[50:65], v[172:175], v[162:165], v[50:65]
	ds_read_b64_tr_b16 v[106:107], v213 offset:43008
	ds_read_b64_tr_b16 v[108:109], v213 offset:43520
	v_add_f32_e32 v110, v68, v123
	v_add_f32_e32 v110, v69, v110
	v_add_f32_e32 v110, v70, v110
	v_add_f32_e32 v110, v71, v110
	v_cvt_pk_bf16_f32 v150, v66, v67
	v_cvt_pk_bf16_f32 v151, v68, v69
	ds_read_b64_tr_b16 v[66:67], v213 offset:47104
	ds_read_b64_tr_b16 v[68:69], v213 offset:47616
	v_add_f32_e32 v110, v72, v110
	v_add_f32_e32 v110, v73, v110
	v_add_f32_e32 v110, v74, v110
	v_add_f32_e32 v123, v75, v110
	v_cvt_pk_bf16_f32 v152, v70, v71
	v_cvt_pk_bf16_f32 v153, v72, v73
	ds_read_b64_tr_b16 v[110:111], v213 offset:44032
	ds_read_b64_tr_b16 v[112:113], v213 offset:44544
	v_add_f32_e32 v70, v76, v123
	v_add_f32_e32 v70, v77, v70
	v_add_f32_e32 v70, v78, v70
	v_add_f32_e32 v123, v79, v70
	v_cvt_pk_bf16_f32 v146, v74, v75
	v_cvt_pk_bf16_f32 v147, v76, v77
	ds_read_b64_tr_b16 v[70:71], v213 offset:48128
	ds_read_b64_tr_b16 v[72:73], v213 offset:48640
	v_add_f32_e32 v74, v80, v123
	v_add_f32_e32 v74, v81, v74
	v_add_f32_e32 v74, 0, v74
	v_cvt_pk_bf16_f32 v148, v78, v79
	v_cvt_pk_bf16_f32 v149, v80, v81
	v_exp_f32_e32 v82, v82
	v_exp_f32_e32 v83, v83
	v_exp_f32_e32 v84, v84
	v_exp_f32_e32 v85, v85
	s_nop 0
	v_exp_f32_e32 v86, v86
	v_exp_f32_e32 v87, v87
	v_exp_f32_e32 v88, v88
	v_exp_f32_e32 v89, v89
	s_nop 0
	v_exp_f32_e32 v90, v90
	v_exp_f32_e32 v91, v91
	v_exp_f32_e32 v92, v92
	v_exp_f32_e32 v93, v93
	s_nop 0
	v_exp_f32_e32 v94, v94
	v_exp_f32_e32 v95, v95
	v_exp_f32_e32 v96, v96
	v_exp_f32_e32 v97, v97
	v_exp_f32_e32 v50, v50
	v_exp_f32_e32 v51, v51
	v_exp_f32_e32 v52, v52
	v_exp_f32_e32 v53, v53
	s_nop 0
	v_exp_f32_e32 v54, v54
	v_exp_f32_e32 v55, v55
	v_exp_f32_e32 v56, v56
	v_exp_f32_e32 v57, v57
	s_nop 0
	v_exp_f32_e32 v58, v58
	v_exp_f32_e32 v59, v59
	v_exp_f32_e32 v60, v60
	v_exp_f32_e32 v61, v61
	s_nop 0
	v_exp_f32_e32 v62, v62
	v_exp_f32_e32 v63, v63
	v_exp_f32_e32 v64, v64
	v_exp_f32_e32 v65, v65
	s_waitcnt lgkmcnt(14)
	v_mfma_f32_32x32x16_bf16 v[18:33], v[158:161], v[114:117], v[18:33]
	v_add_f32_e32 v75, v82, v83
	v_add_f32_e32 v75, v84, v75
	v_add_f32_e32 v75, v85, v75
	v_add_f32_e32 v75, v86, v75
	v_add_f32_e32 v75, v87, v75
	v_add_f32_e32 v75, v88, v75
	v_add_f32_e32 v75, v89, v75
	s_waitcnt lgkmcnt(12)
	v_mfma_f32_32x32x16_bf16 v[34:49], v[158:161], v[98:101], v[34:49]
	v_add_f32_e32 v75, v90, v75
	v_add_f32_e32 v75, v91, v75
	v_add_f32_e32 v75, v92, v75
	v_add_f32_e32 v75, v93, v75
	v_add_f32_e32 v75, v94, v75
	v_add_f32_e32 v75, v95, v75
	v_add_f32_e32 v75, v96, v75
	s_waitcnt lgkmcnt(10)
	v_mfma_f32_32x32x16_bf16 v[18:33], v[154:157], v[118:121], v[18:33]
	v_add_f32_e32 v75, v97, v75
	v_add_f32_e32 v75, v50, v75
	v_add_f32_e32 v75, v51, v75
	v_add_f32_e32 v75, v52, v75
	v_add_f32_e32 v75, v53, v75
	v_add_f32_e32 v75, v54, v75
	v_add_f32_e32 v75, v55, v75
	s_waitcnt lgkmcnt(8)
	v_mfma_f32_32x32x16_bf16 v[34:49], v[154:157], v[102:105], v[34:49]
	v_add_f32_e32 v75, v56, v75
	v_add_f32_e32 v75, v57, v75
	v_add_f32_e32 v75, v58, v75
	v_add_f32_e32 v75, v59, v75
	v_add_f32_e32 v75, v60, v75
	v_add_f32_e32 v75, v61, v75
	v_add_f32_e32 v75, v62, v75
	s_waitcnt lgkmcnt(6)
	v_mfma_f32_32x32x16_bf16 v[18:33], v[150:153], v[106:109], v[18:33]
	v_add_f32_e32 v75, v63, v75
	v_add_f32_e32 v75, v64, v75
	v_add_f32_e32 v75, v65, v75
	v_add_f32_e32 v74, v122, v74
	v_add_f32_e32 v74, v74, v75
	v_cvt_pk_bf16_f32 v76, v82, v83
	v_cvt_pk_bf16_f32 v77, v84, v85
	s_waitcnt lgkmcnt(4)
	v_mfma_f32_32x32x16_bf16 v[34:49], v[150:153], v[66:69], v[34:49]
	v_cvt_pk_bf16_f32 v78, v86, v87
	v_cvt_pk_bf16_f32 v79, v88, v89
	v_cvt_pk_bf16_f32 v80, v90, v91
	v_cvt_pk_bf16_f32 v81, v92, v93
	v_cvt_pk_bf16_f32 v82, v94, v95
	v_cvt_pk_bf16_f32 v83, v96, v97
	v_cvt_pk_bf16_f32 v50, v50, v51
	s_waitcnt lgkmcnt(2)
	v_mfma_f32_32x32x16_bf16 v[18:33], v[146:149], v[110:113], v[18:33]
	v_cvt_pk_bf16_f32 v51, v52, v53
	v_cvt_pk_bf16_f32 v52, v54, v55
	v_cvt_pk_bf16_f32 v53, v56, v57
	v_cvt_pk_bf16_f32 v54, v58, v59
	v_cvt_pk_bf16_f32 v55, v60, v61
	v_cvt_pk_bf16_f32 v56, v62, v63
	v_cvt_pk_bf16_f32 v57, v64, v65
	s_waitcnt lgkmcnt(0)
; __device__ __forceinline__ int crow(int r,int hi){return (r&3)+8*(r>>2)+4*hi;}
; #define SBAR() __builtin_amdgcn_sched_barrier(0)
; __device__ __forceinline__ void pv(f32x16*o,int vb,bf16x8 pa0,bf16x8 pa1,bf16x8 pa2,bf16x8 pa3){
;     ...
;       asm volatile("ds_read_b64_tr_b16 %0,%1 offset:%c2":"=&v"(lo[ks]):"v"(vb),"i"(d0*4096+ks*1024):"memory");
;       asm volatile("ds_read_b64_tr_b16 %0,%1 offset:%c2":"=&v"(hi[ks]):"v"(vb),"i"(d0*4096+ks*1024+512):"memory");}
;     asm volatile("s_waitcnt lgkmcnt(0)":::"memory");SBAR();
;     ...
;     o[d0]=__builtin_amdgcn_mfma_f32_32x32x16_bf16(pa0,PK(0),o[d0],0,0,0);
;     o[d0]=__builtin_amdgcn_mfma_f32_32x32x16_bf16(pa1,PK(1),o[d0],0,0,0);
;     o[d0]=__builtin_amdgcn_mfma_f32_32x32x16_bf16(pa2,PK(2),o[d0],0,0,0);
;     o[d0]=__builtin_amdgcn_mfma_f32_32x32x16_bf16(pa3,PK(3),o[d0],0,0,0);
; template<int THRL,bool FIXREF,bool HALFK> __device__ __forceinline__ void attn_unit(float mref,long rowbase,int q0,const bf16*Qh,int PQ,const bf16*__restrict__ Kh_,int PK,const bf16*__restrict__ Vh_,int PV,bf16*Oh,int PO,const bf16*Gh,int PG,u32x4(&okeep)[4],int omode,float lam,float oml,const float ...
;     ...
;   {auto rr=__builtin_amdgcn_permlane32_swap(__float_as_uint(l_reg),__float_as_uint(l_reg),false,false);l_reg=__uint_as_float(rr[0])+__uint_as_float(rr[1]);}
;   if(hi==0)wsf[32+r32]=l_reg;asm volatile("s_waitcnt lgkmcnt(0)":::"memory");
;   float rli[16];
;   #pragma unroll
;   for(int r=0;r<16;++r)rli[r]=__builtin_amdgcn_rcpf(wsf[32+crow(r,hi)]);
;   bf16*Ow=Oh+(rowbase+q0+wid*QBLK)*PO;
;   { bf16*stg=(bf16*)(shm+LDS_OST)+wid*2048;
;     #pragma unroll
;     for(int r=0;r<16;++r){const int orow=crow(r,hi);
;       #pragma unroll
;       for(int d0=0;d0<2;++d0)stg[orow*64+d0*32+r32]=__float2bfloat16(o[d0][r]*rli[r]);}
;     asm volatile("s_waitcnt lgkmcnt(0)":::"memory");
	v_mfma_f32_32x32x16_bf16 v[34:49], v[146:149], v[70:73], v[34:49]
	ds_read_b64_tr_b16 v[58:59],v0 offset:0
	ds_read_b64_tr_b16 v[60:61],v0 offset:512
	ds_read_b64_tr_b16 v[62:63],v0 offset:1024
	ds_read_b64_tr_b16 v[64:65],v0 offset:1536
	ds_read_b64_tr_b16 v[66:67],v0 offset:2048
	ds_read_b64_tr_b16 v[68:69],v0 offset:2560
	ds_read_b64_tr_b16 v[70:71],v0 offset:3072
	ds_read_b64_tr_b16 v[72:73],v0 offset:3584
	s_waitcnt lgkmcnt(0)
	s_nop 0
	v_mfma_f32_32x32x16_bf16 v[18:33], v[76:79], v[58:61], v[18:33]
	ds_read_b64_tr_b16 v[58:59],v0 offset:4096
	ds_read_b64_tr_b16 v[60:61],v0 offset:4608
	v_mfma_f32_32x32x16_bf16 v[18:33], v[80:83], v[62:65], v[18:33]
	ds_read_b64_tr_b16 v[62:63],v0 offset:5120
	ds_read_b64_tr_b16 v[64:65],v0 offset:5632
	v_mfma_f32_32x32x16_bf16 v[18:33], v[50:53], v[66:69], v[18:33]
	ds_read_b64_tr_b16 v[66:67],v0 offset:6144
	ds_read_b64_tr_b16 v[68:69],v0 offset:6656
	v_mfma_f32_32x32x16_bf16 v[18:33], v[54:57], v[70:73], v[18:33]
	ds_read_b64_tr_b16 v[70:71],v0 offset:7168
	ds_read_b64_tr_b16 v[72:73],v0 offset:7680
	s_waitcnt lgkmcnt(0)
	v_mfma_f32_32x32x16_bf16 v[34:49], v[76:79], v[58:61], v[34:49]
	v_mov_b32_e32 v0, v74
	s_nop 1
	v_permlane32_swap_b32_e32 v74, v0
	v_cmp_gt_u32_e32 vcc, 32, v209
	v_mfma_f32_32x32x16_bf16 v[34:49], v[80:83], v[62:65], v[34:49]
	v_mfma_f32_32x32x16_bf16 v[34:49], v[50:53], v[66:69], v[34:49]
	v_mfma_f32_32x32x16_bf16 v[34:49], v[54:57], v[70:73], v[34:49]
	s_and_saveexec_b64 s[48:49], vcc
	v_lshl_add_u32 v50, v171, 2, s20
	v_add_f32_e32 v0, v74, v0
	ds_write_b32 v50, v0 offset:49280
	s_or_b64 exec, exec, s[48:49]
	s_waitcnt lgkmcnt(0)
	v_lshl_add_u32 v0, v212, 4, s20
	ds_read_b128 v[50:53], v0 offset:49280
	ds_read_b128 v[54:57], v0 offset:49312
	s_lshl_b32 s20, s79, 12
	s_add_i32 s20, s20, 0
	v_lshlrev_b32_e32 v66, 1, v171
	s_waitcnt lgkmcnt(1)
	v_rcp_f32_e32 v58, v50
	v_rcp_f32_e32 v59, v51
	v_rcp_f32_e32 v60, v52
	v_rcp_f32_e32 v61, v53
	s_waitcnt lgkmcnt(0)
	v_rcp_f32_e32 v62, v54
	ds_read_b128 v[50:53], v0 offset:49344
	v_rcp_f32_e32 v63, v55
	v_rcp_f32_e32 v64, v56
	v_rcp_f32_e32 v65, v57
	ds_read_b128 v[54:57], v0 offset:49376
	s_waitcnt lgkmcnt(1)
	v_rcp_f32_e32 v0, v50
	v_rcp_f32_e32 v50, v51
	v_rcp_f32_e32 v51, v52
	v_rcp_f32_e32 v52, v53
	s_waitcnt lgkmcnt(0)
	v_rcp_f32_e32 v53, v54
	v_rcp_f32_e32 v54, v55
	v_rcp_f32_e32 v55, v56
	v_rcp_f32_e32 v56, v57
	v_lshlrev_b32_e32 v57, 9, v212
	v_mul_f32_e32 v18, v18, v58
	v_add3_u32 v57, s20, v57, v66
	v_cvt_pk_bf16_f32 v18, v18, s0
	ds_write_b16 v57, v18 offset:51200
	v_mul_f32_e32 v18, v34, v58
	v_cvt_pk_bf16_f32 v18, v18, s0
	ds_write_b16 v57, v18 offset:51264
	v_mul_f32_e32 v18, v19, v59
	v_cvt_pk_bf16_f32 v18, v18, s0
	ds_write_b16 v57, v18 offset:51328
	v_mul_f32_e32 v18, v35, v59
	v_cvt_pk_bf16_f32 v18, v18, s0
	ds_write_b16 v57, v18 offset:51392
	v_mul_f32_e32 v18, v20, v60
	v_cvt_pk_bf16_f32 v18, v18, s0
	ds_write_b16 v57, v18 offset:51456
	v_mul_f32_e32 v18, v36, v60
	v_cvt_pk_bf16_f32 v18, v18, s0
	ds_write_b16 v57, v18 offset:51520
	v_mul_f32_e32 v18, v21, v61
	v_cvt_pk_bf16_f32 v18, v18, s0
	ds_write_b16 v57, v18 offset:51584
	v_mul_f32_e32 v18, v37, v61
	v_cvt_pk_bf16_f32 v18, v18, s0
	ds_write_b16 v57, v18 offset:51648
	v_mul_f32_e32 v18, v22, v62
	v_cvt_pk_bf16_f32 v18, v18, s0
	ds_write_b16 v57, v18 offset:52224
	v_mul_f32_e32 v18, v38, v62
	v_cvt_pk_bf16_f32 v18, v18, s0
	ds_write_b16 v57, v18 offset:52288
	v_mul_f32_e32 v18, v23, v63
	v_cvt_pk_bf16_f32 v18, v18, s0
	ds_write_b16 v57, v18 offset:52352
	v_mul_f32_e32 v18, v39, v63
	v_cvt_pk_bf16_f32 v18, v18, s0
	ds_write_b16 v57, v18 offset:52416
	v_mul_f32_e32 v18, v24, v64
	v_cvt_pk_bf16_f32 v18, v18, s0
	ds_write_b16 v57, v18 offset:52480
	v_mul_f32_e32 v18, v40, v64
	v_cvt_pk_bf16_f32 v18, v18, s0
	ds_write_b16 v57, v18 offset:52544
	v_mul_f32_e32 v18, v25, v65
	v_cvt_pk_bf16_f32 v18, v18, s0
	ds_write_b16 v57, v18 offset:52608
	v_mul_f32_e32 v18, v41, v65
	v_cvt_pk_bf16_f32 v18, v18, s0
	ds_write_b16 v57, v18 offset:52672
	v_mul_f32_e32 v18, v26, v0
	v_mul_f32_e32 v0, v42, v0
	v_cvt_pk_bf16_f32 v0, v0, s0
	ds_write_b16 v57, v0 offset:53312
	v_mul_f32_e32 v0, v27, v50
	v_cvt_pk_bf16_f32 v0, v0, s0
	ds_write_b16 v57, v0 offset:53376
	v_mul_f32_e32 v0, v43, v50
	v_cvt_pk_bf16_f32 v0, v0, s0
	ds_write_b16 v57, v0 offset:53440
	v_mul_f32_e32 v0, v28, v51
	v_cvt_pk_bf16_f32 v0, v0, s0
	ds_write_b16 v57, v0 offset:53504
	v_mul_f32_e32 v0, v44, v51
	v_cvt_pk_bf16_f32 v0, v0, s0
	ds_write_b16 v57, v0 offset:53568
	v_mul_f32_e32 v0, v29, v52
	v_cvt_pk_bf16_f32 v0, v0, s0
	ds_write_b16 v57, v0 offset:53632
	v_mul_f32_e32 v0, v45, v52
	v_cvt_pk_bf16_f32 v0, v0, s0
	ds_write_b16 v57, v0 offset:53696
	v_mul_f32_e32 v0, v30, v53
	v_cvt_pk_bf16_f32 v0, v0, s0
	ds_write_b16 v57, v0 offset:54272
	v_mul_f32_e32 v0, v46, v53
	v_cvt_pk_bf16_f32 v0, v0, s0
	ds_write_b16 v57, v0 offset:54336
	v_mul_f32_e32 v0, v31, v54
	v_cvt_pk_bf16_f32 v0, v0, s0
	ds_write_b16 v57, v0 offset:54400
	v_mul_f32_e32 v0, v47, v54
	v_cvt_pk_bf16_f32 v0, v0, s0
	ds_write_b16 v57, v0 offset:54464
	v_mul_f32_e32 v0, v32, v55
	v_cvt_pk_bf16_f32 v0, v0, s0
	ds_write_b16 v57, v0 offset:54528
	v_mul_f32_e32 v0, v48, v55
	v_cvt_pk_bf16_f32 v0, v0, s0
	ds_write_b16 v57, v0 offset:54592
	v_mul_f32_e32 v0, v33, v56
	v_cvt_pk_bf16_f32 v0, v0, s0
	ds_write_b16 v57, v0 offset:54656
	v_mul_f32_e32 v0, v49, v56
	v_cvt_pk_bf16_f32 v18, v18, s0
	v_cvt_pk_bf16_f32 v0, v0, s0
	ds_write_b16 v57, v18 offset:53248
	ds_write_b16 v57, v0 offset:54720
	s_lshl_b64 s[46:47], s[46:47], 11
	s_waitcnt lgkmcnt(0)
	s_add_u32 s46, s69, s46
	s_addc_u32 s47, s70, s47
	s_mov_b64 s[48:49], -1
	s_and_b64 vcc, exec, s[42:43]
	s_cbranch_vccz .LBB0_470
; __device__ __forceinline__ unsigned cvtpk_s(float lo,float hi){f32x2_t v={lo,hi};bf16x2_t b=__builtin_convertvector(v,bf16x2_t);return __builtin_bit_cast(unsigned,b);}
; template<int THRL,bool FIXREF,bool HALFK> __device__ __forceinline__ void attn_unit(float mref,long rowbase,int q0,const bf16*Qh,int PQ,const bf16*__restrict__ Kh_,int PK,const bf16*__restrict__ Vh_,int PV,bf16*Oh,int PO,const bf16*Gh,int PG,u32x4(&okeep)[4],int omode,float lam,float oml,const float ...
;     ...
;     else if(Gh){
;       u32x4 gv[4]; const char*gst=shm+LDS_GST+wid*4096+lane*16;
;       #pragma unroll
;       for(int i=0;i<4;++i) gv[i]=*(const u32x4*)(gst+i*1024);
;       #pragma unroll
;       for(int i=0;i<4;++i){const int row=i*8+(lane>>3),ch=lane&7; u32x4 v=*(const u32x4*)(stg+row*64+ch*8);
;         #pragma unroll
;         for(int k=0;k<4;++k){ const float g0=__uint_as_float(gv[i][k]<<16),g1=__uint_as_float(gv[i][k]&0xffff0000u),o0=__uint_as_float(v[k]<<16),o1=__uint_as_float(v[k]&0xffff0000u);
;           v[k]=cvtpk_s(o0*g0*__builtin_amdgcn_rcpf(1.f+__builtin_amdgcn_exp2f(-1.4426950408889634f*g0)),o1*g1*__builtin_amdgcn_rcpf(1.f+__builtin_amdgcn_exp2f(-1.4426950408889634f*g1))); }
;         ATTN_STORE16(Ow+(long)row*PO+ch*8,v);} }
	s_mov_b64 s[42:43], -1
	s_and_b64 vcc, exec, s[40:41]
	s_cbranch_vccz .LBB0_467
	v_lshl_add_u32 v0, v209, 4, s20
	v_add_u32_e32 v0, 0x14800, v0
	ds_read_b128 v[30:33], v0
	ds_read_b128 v[26:29], v0 offset:1024
	ds_read_b128 v[22:25], v0 offset:2048
	ds_read_b128 v[18:21], v0 offset:3072
	v_lshlrev_b32_e32 v0, 1, v211
	v_and_b32_e32 v0, 0x70, v0
	v_add_u32_e32 v36, s20, v0
	v_lshl_add_u64 v[34:35], s[46:47], 0, v[0:1]
	v_lshl_add_u32 v0, v208, 7, v36
	s_waitcnt lgkmcnt(3)
	v_lshlrev_b32_e32 v44, 16, v30
	ds_read_b128 v[38:41], v0 offset:51200
	v_mul_f32_e32 v0, 0xbfb8aa3b, v44
	v_exp_f32_e32 v0, v0
	v_and_b32_e32 v43, 0xffff0000, v30
	s_mov_b64 s[42:43], 0
	s_waitcnt lgkmcnt(0)
	v_lshlrev_b32_e32 v42, 16, v38
	v_add_f32_e32 v0, 1.0, v0
	v_rcp_f32_e32 v46, v0
	v_mul_f32_e32 v0, 0xbfb8aa3b, v43
	v_exp_f32_e32 v0, v0
	v_and_b32_e32 v45, 0xffff0000, v38
	v_lshlrev_b32_e32 v38, 16, v31
	v_pk_mul_f32 v[44:45], v[42:43], v[44:45]
	v_add_f32_e32 v0, 1.0, v0
	v_rcp_f32_e32 v47, v0
	v_mul_f32_e32 v0, 0xbfb8aa3b, v38
	v_exp_f32_e32 v0, v0
	v_pk_mul_f32 v[42:43], v[46:47], v[44:45]
	s_nop 0
	v_cvt_pk_bf16_f32 v30, v42, v43
	v_and_b32_e32 v43, 0xffff0000, v31
	v_add_f32_e32 v0, 1.0, v0
	v_rcp_f32_e32 v44, v0
	v_mul_f32_e32 v0, 0xbfb8aa3b, v43
	v_exp_f32_e32 v0, v0
	v_lshlrev_b32_e32 v42, 16, v39
	v_and_b32_e32 v39, 0xffff0000, v39
	v_pk_mul_f32 v[38:39], v[42:43], v[38:39]
	v_add_f32_e32 v0, 1.0, v0
	v_lshlrev_b32_e32 v42, 16, v32
	v_rcp_f32_e32 v45, v0
	v_mul_f32_e32 v0, 0xbfb8aa3b, v42
	v_exp_f32_e32 v0, v0
	v_and_b32_e32 v43, 0xffff0000, v40
	v_pk_mul_f32 v[38:39], v[44:45], v[38:39]
	v_add_f32_e32 v0, 1.0, v0
	v_cvt_pk_bf16_f32 v31, v38, v39
	v_and_b32_e32 v39, 0xffff0000, v32
	v_rcp_f32_e32 v44, v0
	v_mul_f32_e32 v0, 0xbfb8aa3b, v39
	v_exp_f32_e32 v0, v0
	v_lshlrev_b32_e32 v38, 16, v40
	v_lshlrev_b32_e32 v40, 16, v33
	v_pk_mul_f32 v[42:43], v[38:39], v[42:43]
	v_add_f32_e32 v0, 1.0, v0
	v_rcp_f32_e32 v45, v0
	v_mul_f32_e32 v0, 0xbfb8aa3b, v40
	v_exp_f32_e32 v0, v0
	v_pk_mul_f32 v[38:39], v[44:45], v[42:43]
	s_nop 0
	v_cvt_pk_bf16_f32 v32, v38, v39
	v_and_b32_e32 v39, 0xffff0000, v33
	v_add_f32_e32 v0, 1.0, v0
	v_rcp_f32_e32 v42, v0
	v_mul_f32_e32 v0, 0xbfb8aa3b, v39
	v_exp_f32_e32 v0, v0
	v_lshlrev_b32_e32 v38, 16, v41
	v_and_b32_e32 v41, 0xffff0000, v41
	v_pk_mul_f32 v[40:41], v[38:39], v[40:41]
	v_add_f32_e32 v0, 1.0, v0
	v_rcp_f32_e32 v43, v0
	v_lshlrev_b32_e32 v0, 11, v208
	v_pk_mul_f32 v[38:39], v[42:43], v[40:41]
	s_nop 0
	v_cvt_pk_bf16_f32 v33, v38, v39
	v_lshl_add_u64 v[38:39], v[34:35], 0, v[0:1]
	v_lshlrev_b32_e32 v40, 16, v26
	global_store_dwordx4 v[38:39], v[30:33], off
	v_and_b32_e32 v39, 0xffff0000, v26
	v_mul_f32_e32 v26, 0xbfb8aa3b, v40
	v_exp_f32_e32 v26, v26
	v_or_b32_e32 v0, 8, v208
	v_lshl_add_u32 v30, v0, 7, v36
	ds_read_b128 v[30:33], v30 offset:51200
	v_add_f32_e32 v26, 1.0, v26
	v_rcp_f32_e32 v42, v26
	v_mul_f32_e32 v26, 0xbfb8aa3b, v39
	v_exp_f32_e32 v26, v26
	s_waitcnt lgkmcnt(0)
	v_lshlrev_b32_e32 v38, 16, v30
	v_and_b32_e32 v41, 0xffff0000, v30
	v_pk_mul_f32 v[40:41], v[38:39], v[40:41]
	v_add_f32_e32 v26, 1.0, v26
	v_rcp_f32_e32 v43, v26
	v_lshlrev_b32_e32 v30, 16, v27
	v_lshlrev_b32_e32 v0, 11, v0
	v_pk_mul_f32 v[38:39], v[42:43], v[40:41]
	s_nop 0
	v_cvt_pk_bf16_f32 v26, v38, v39
	v_and_b32_e32 v39, 0xffff0000, v27
	v_mul_f32_e32 v27, 0xbfb8aa3b, v30
	v_exp_f32_e32 v27, v27
	v_lshlrev_b32_e32 v38, 16, v31
	v_and_b32_e32 v31, 0xffff0000, v31
	v_pk_mul_f32 v[30:31], v[38:39], v[30:31]
	v_add_f32_e32 v27, 1.0, v27
	v_rcp_f32_e32 v40, v27
	v_mul_f32_e32 v27, 0xbfb8aa3b, v39
	v_exp_f32_e32 v27, v27
	v_lshlrev_b32_e32 v38, 16, v28
	v_and_b32_e32 v39, 0xffff0000, v32
	v_add_f32_e32 v27, 1.0, v27
	v_rcp_f32_e32 v41, v27
	s_nop 0
	v_pk_mul_f32 v[30:31], v[40:41], v[30:31]
	s_nop 0
	v_cvt_pk_bf16_f32 v27, v30, v31
	v_and_b32_e32 v31, 0xffff0000, v28
	v_mul_f32_e32 v28, 0xbfb8aa3b, v38
	v_exp_f32_e32 v28, v28
	v_lshlrev_b32_e32 v30, 16, v32
	v_pk_mul_f32 v[38:39], v[30:31], v[38:39]
	v_lshlrev_b32_e32 v32, 16, v29
	v_add_f32_e32 v28, 1.0, v28
	v_rcp_f32_e32 v40, v28
	v_mul_f32_e32 v28, 0xbfb8aa3b, v31
	v_exp_f32_e32 v28, v28
	s_nop 0
	v_add_f32_e32 v28, 1.0, v28
	v_rcp_f32_e32 v41, v28
	s_nop 0
	v_pk_mul_f32 v[30:31], v[40:41], v[38:39]
	s_nop 0
	v_cvt_pk_bf16_f32 v28, v30, v31
	v_and_b32_e32 v31, 0xffff0000, v29
	v_mul_f32_e32 v29, 0xbfb8aa3b, v32
	v_exp_f32_e32 v29, v29
	v_lshlrev_b32_e32 v30, 16, v33
	v_and_b32_e32 v33, 0xffff0000, v33
	v_pk_mul_f32 v[32:33], v[30:31], v[32:33]
	v_add_f32_e32 v29, 1.0, v29
	v_rcp_f32_e32 v38, v29
	v_mul_f32_e32 v29, 0xbfb8aa3b, v31
	v_exp_f32_e32 v29, v29
	s_nop 0
	v_add_f32_e32 v29, 1.0, v29
	v_rcp_f32_e32 v39, v29
	s_nop 0
	v_pk_mul_f32 v[30:31], v[38:39], v[32:33]
	s_nop 0
	v_cvt_pk_bf16_f32 v29, v30, v31
	v_lshl_add_u64 v[30:31], v[34:35], 0, v[0:1]
	v_lshlrev_b32_e32 v32, 16, v22
	global_store_dwordx4 v[30:31], v[26:29], off
	v_and_b32_e32 v31, 0xffff0000, v22
	v_mul_f32_e32 v22, 0xbfb8aa3b, v32
	v_exp_f32_e32 v22, v22
	v_or_b32_e32 v0, 16, v208
	v_lshl_add_u32 v26, v0, 7, v36
	ds_read_b128 v[26:29], v26 offset:51200
	v_add_f32_e32 v22, 1.0, v22
	v_rcp_f32_e32 v38, v22
	v_mul_f32_e32 v22, 0xbfb8aa3b, v31
	v_exp_f32_e32 v22, v22
	s_waitcnt lgkmcnt(0)
; __device__ __forceinline__ unsigned cvtpk_s(float lo,float hi){f32x2_t v={lo,hi};bf16x2_t b=__builtin_convertvector(v,bf16x2_t);return __builtin_bit_cast(unsigned,b);}
; template<int THRL,bool FIXREF,bool HALFK> __device__ __forceinline__ void attn_unit(float mref,long rowbase,int q0,const bf16*Qh,int PQ,const bf16*__restrict__ Kh_,int PK,const bf16*__restrict__ Vh_,int PV,bf16*Oh,int PO,const bf16*Gh,int PG,u32x4(&okeep)[4],int omode,float lam,float oml,const float ...
;     ...
;       for(int i=0;i<4;++i){const int row=i*8+(lane>>3),ch=lane&7; u32x4 v=*(const u32x4*)(stg+row*64+ch*8);
;         #pragma unroll
;         for(int k=0;k<4;++k){ const float g0=__uint_as_float(gv[i][k]<<16),g1=__uint_as_float(gv[i][k]&0xffff0000u),o0=__uint_as_float(v[k]<<16),o1=__uint_as_float(v[k]&0xffff0000u);
;           v[k]=cvtpk_s(o0*g0*__builtin_amdgcn_rcpf(1.f+__builtin_amdgcn_exp2f(-1.4426950408889634f*g0)),o1*g1*__builtin_amdgcn_rcpf(1.f+__builtin_amdgcn_exp2f(-1.4426950408889634f*g1))); }
;         ATTN_STORE16(Ow+(long)row*PO+ch*8,v);} }
	v_lshlrev_b32_e32 v30, 16, v26
	v_and_b32_e32 v33, 0xffff0000, v26
	v_pk_mul_f32 v[32:33], v[30:31], v[32:33]
	v_add_f32_e32 v22, 1.0, v22
	v_rcp_f32_e32 v39, v22
	v_lshlrev_b32_e32 v26, 16, v23
	v_lshlrev_b32_e32 v0, 11, v0
	v_pk_mul_f32 v[30:31], v[38:39], v[32:33]
	s_nop 0
	v_cvt_pk_bf16_f32 v22, v30, v31
	v_and_b32_e32 v31, 0xffff0000, v23
	v_mul_f32_e32 v23, 0xbfb8aa3b, v26
	v_exp_f32_e32 v23, v23
	v_lshlrev_b32_e32 v30, 16, v27
	v_and_b32_e32 v27, 0xffff0000, v27
	v_pk_mul_f32 v[26:27], v[30:31], v[26:27]
	v_add_f32_e32 v23, 1.0, v23
	v_rcp_f32_e32 v32, v23
	v_mul_f32_e32 v23, 0xbfb8aa3b, v31
	v_exp_f32_e32 v23, v23
	v_lshlrev_b32_e32 v30, 16, v24
	v_and_b32_e32 v31, 0xffff0000, v28
	v_add_f32_e32 v23, 1.0, v23
	v_rcp_f32_e32 v33, v23
	s_nop 0
	v_pk_mul_f32 v[26:27], v[32:33], v[26:27]
	s_nop 0
	v_cvt_pk_bf16_f32 v23, v26, v27
	v_and_b32_e32 v27, 0xffff0000, v24
	v_mul_f32_e32 v24, 0xbfb8aa3b, v30
	v_exp_f32_e32 v24, v24
	v_lshlrev_b32_e32 v26, 16, v28
	v_pk_mul_f32 v[30:31], v[26:27], v[30:31]
	v_lshlrev_b32_e32 v28, 16, v25
	v_add_f32_e32 v24, 1.0, v24
	v_rcp_f32_e32 v32, v24
	v_mul_f32_e32 v24, 0xbfb8aa3b, v27
	v_exp_f32_e32 v24, v24
	s_nop 0
	v_add_f32_e32 v24, 1.0, v24
	v_rcp_f32_e32 v33, v24
	s_nop 0
	v_pk_mul_f32 v[26:27], v[32:33], v[30:31]
	s_nop 0
	v_cvt_pk_bf16_f32 v24, v26, v27
	v_and_b32_e32 v27, 0xffff0000, v25
	v_mul_f32_e32 v25, 0xbfb8aa3b, v28
	v_exp_f32_e32 v25, v25
	v_lshlrev_b32_e32 v26, 16, v29
	v_and_b32_e32 v29, 0xffff0000, v29
	v_pk_mul_f32 v[28:29], v[26:27], v[28:29]
	v_add_f32_e32 v25, 1.0, v25
	v_rcp_f32_e32 v30, v25
	v_mul_f32_e32 v25, 0xbfb8aa3b, v27
	v_exp_f32_e32 v25, v25
	s_nop 0
	v_add_f32_e32 v25, 1.0, v25
	v_rcp_f32_e32 v31, v25
	s_nop 0
	v_pk_mul_f32 v[26:27], v[30:31], v[28:29]
	s_nop 0
	v_cvt_pk_bf16_f32 v25, v26, v27
	v_lshl_add_u64 v[26:27], v[34:35], 0, v[0:1]
	v_lshlrev_b32_e32 v28, 16, v18
	global_store_dwordx4 v[26:27], v[22:25], off
	v_and_b32_e32 v27, 0xffff0000, v18
	v_mul_f32_e32 v18, 0xbfb8aa3b, v28
	v_exp_f32_e32 v18, v18
	v_or_b32_e32 v0, 24, v208
	v_lshl_add_u32 v22, v0, 7, v36
	ds_read_b128 v[22:25], v22 offset:51200
	v_add_f32_e32 v18, 1.0, v18
	v_rcp_f32_e32 v30, v18
	v_mul_f32_e32 v18, 0xbfb8aa3b, v27
	v_exp_f32_e32 v18, v18
	s_waitcnt lgkmcnt(0)
	v_lshlrev_b32_e32 v26, 16, v22
	v_and_b32_e32 v29, 0xffff0000, v22
	v_pk_mul_f32 v[28:29], v[26:27], v[28:29]
	v_add_f32_e32 v18, 1.0, v18
	v_rcp_f32_e32 v31, v18
	v_lshlrev_b32_e32 v22, 16, v19
	v_lshlrev_b32_e32 v0, 11, v0
	v_pk_mul_f32 v[26:27], v[30:31], v[28:29]
	s_nop 0
	v_cvt_pk_bf16_f32 v18, v26, v27
	v_and_b32_e32 v27, 0xffff0000, v19
	v_mul_f32_e32 v19, 0xbfb8aa3b, v22
	v_exp_f32_e32 v19, v19
	v_lshlrev_b32_e32 v26, 16, v23
	v_and_b32_e32 v23, 0xffff0000, v23
	v_pk_mul_f32 v[22:23], v[26:27], v[22:23]
	v_add_f32_e32 v19, 1.0, v19
	v_rcp_f32_e32 v28, v19
	v_mul_f32_e32 v19, 0xbfb8aa3b, v27
	v_exp_f32_e32 v19, v19
	v_lshlrev_b32_e32 v26, 16, v20
	v_and_b32_e32 v27, 0xffff0000, v24
	v_add_f32_e32 v19, 1.0, v19
	v_rcp_f32_e32 v29, v19
	s_nop 0
	v_pk_mul_f32 v[22:23], v[28:29], v[22:23]
	s_nop 0
	v_cvt_pk_bf16_f32 v19, v22, v23
	v_and_b32_e32 v23, 0xffff0000, v20
	v_mul_f32_e32 v20, 0xbfb8aa3b, v26
	v_exp_f32_e32 v20, v20
	v_lshlrev_b32_e32 v22, 16, v24
	v_pk_mul_f32 v[26:27], v[22:23], v[26:27]
	v_lshlrev_b32_e32 v24, 16, v21
	v_add_f32_e32 v20, 1.0, v20
	v_rcp_f32_e32 v28, v20
	v_mul_f32_e32 v20, 0xbfb8aa3b, v23
	v_exp_f32_e32 v20, v20
	s_nop 0
	v_add_f32_e32 v20, 1.0, v20
	v_rcp_f32_e32 v29, v20
	s_nop 0
	v_pk_mul_f32 v[22:23], v[28:29], v[26:27]
	s_nop 0
	v_cvt_pk_bf16_f32 v20, v22, v23
	v_and_b32_e32 v23, 0xffff0000, v21
	v_mul_f32_e32 v21, 0xbfb8aa3b, v24
	v_exp_f32_e32 v21, v21
	v_lshlrev_b32_e32 v22, 16, v25
	v_and_b32_e32 v25, 0xffff0000, v25
	v_pk_mul_f32 v[24:25], v[22:23], v[24:25]
	v_add_f32_e32 v21, 1.0, v21
	v_rcp_f32_e32 v26, v21
	v_mul_f32_e32 v21, 0xbfb8aa3b, v23
	v_exp_f32_e32 v21, v21
	s_nop 0
	v_add_f32_e32 v21, 1.0, v21
	v_rcp_f32_e32 v27, v21
	s_nop 0
	v_pk_mul_f32 v[22:23], v[26:27], v[24:25]
	s_nop 0
	v_cvt_pk_bf16_f32 v21, v22, v23
	v_lshl_add_u64 v[22:23], v[34:35], 0, v[0:1]
	global_store_dwordx4 v[22:23], v[18:21], off

; __device__ __forceinline__ void phase_hyena(int l, LAS unsigned char* lds, int G) {
;     ...
;         { int D = Dlo;
;           for (; D < 8 * wave - 59; ++D) HY_BODY(true, false);
;           for (; D <= 8 * wave + 3; ++D) HY_BODY(true, true);
;           for (; D <= Dhi; ++D) HY_BODY(false, true); }
.Lhy_x:
	s_waitcnt lgkmcnt(0)
	s_cmp_ge_i32 s2, s78
	s_cbranch_scc1 .Lhy_x_last
	v_add_u32_e32 v155, 0xffffff80, v155
	v_add_u32_e32 v15, -1, v15
	v_add_u32_e32 v14, 0xffffff80, v14
	v_add_u32_e32 v0, 0xffffff80, v0
	s_add_i32 s2, s2, 1
	v_mov_b64_e32 v[176:177], v[80:81]
	v_mov_b64_e32 v[178:179], v[82:83]
	v_mov_b64_e32 v[180:181], v[6:7]
	v_mov_b64_e32 v[182:183], v[8:9]
	v_add_u32_e32 v156, v155, v128
	v_add_u32_e32 v156, 0x12040, v156
	ds_read2_b32 v[160:161], v156 offset0:0 offset1:1
	ds_read2_b32 v[162:163], v156 offset0:2 offset1:3
	ds_read2_b32 v[164:165], v156 offset0:8 offset1:9
	ds_read2_b32 v[166:167], v156 offset0:10 offset1:11
	ds_read2_b32 v[168:169], v156 offset0:16 offset1:17
	ds_read2_b32 v[170:171], v156 offset0:18 offset1:19
	ds_read2_b32 v[172:173], v156 offset0:24 offset1:25
	ds_read2_b32 v[174:175], v156 offset0:26 offset1:27
	v_cmp_gt_u32_e32 vcc, 64, v15
	v_add_u32_e32 v157, v14, v128
	v_add_u32_e32 v159, 4, v15
	v_cndmask_b32_e32 v157, v227, v157, vcc
	ds_read_b128 v[184:187], v157
	ds_read_b128 v[204:207], v157 offset:32
	ds_read_b128 v[208:211], v157 offset:64
	ds_read_b128 v[212:215], v157 offset:96
	v_cmp_gt_u32_e32 vcc, 64, v159
	v_add_u32_e32 v158, v0, v128
	s_nop 0
	v_cndmask_b32_e32 v158, v227, v158, vcc
	ds_read_b128 v[228:231], v158
	ds_read_b128 v[232:235], v158 offset:32
	ds_read_b128 v[236:239], v158 offset:64
	ds_read_b128 v[240:243], v158 offset:96
	s_setprio 1
	v_mfma_f32_32x32x16_bf16 v[48:63], v[10:13], v[92:95], v[48:63]
	v_mfma_f32_32x32x16_bf16 v[64:79], v[10:13], v[108:111], v[64:79]
	v_mfma_f32_32x32x16_bf16 v[16:31], v[80:83], v[92:95], v[16:31]
	v_mfma_f32_32x32x16_bf16 v[32:47], v[80:83], v[108:111], v[32:47]
	v_mfma_f32_32x32x16_bf16 v[48:63], v[2:5], v[100:103], v[48:63]
	v_mfma_f32_32x32x16_bf16 v[64:79], v[2:5], v[116:119], v[64:79]
	v_mfma_f32_32x32x16_bf16 v[16:31], v[6:9], v[100:103], v[16:31]
	v_mfma_f32_32x32x16_bf16 v[32:47], v[6:9], v[116:119], v[32:47]
	v_mfma_f32_32x32x16_bf16 v[48:63], v[88:91], v[96:99], v[48:63]
	v_mfma_f32_32x32x16_bf16 v[64:79], v[88:91], v[112:115], v[64:79]
	v_mfma_f32_32x32x16_bf16 v[16:31], v[10:13], v[96:99], v[16:31]
	v_mfma_f32_32x32x16_bf16 v[32:47], v[10:13], v[112:115], v[32:47]
	v_mfma_f32_32x32x16_bf16 v[48:63], v[84:87], v[104:107], v[48:63]
	v_mfma_f32_32x32x16_bf16 v[64:79], v[84:87], v[120:123], v[64:79]
	v_mfma_f32_32x32x16_bf16 v[16:31], v[2:5], v[104:107], v[16:31]
	v_mfma_f32_32x32x16_bf16 v[32:47], v[2:5], v[120:123], v[32:47]
	s_setprio 0
	s_waitcnt lgkmcnt(0)
	s_cmp_ge_i32 s2, s78
	s_cbranch_scc1 .Lhy_y_last
	v_add_u32_e32 v155, 0xffffff80, v155
	v_add_u32_e32 v15, -1, v15
	v_add_u32_e32 v14, 0xffffff80, v14
	v_add_u32_e32 v0, 0xffffff80, v0
	s_add_i32 s2, s2, 1
	v_mov_b64_e32 v[88:89], v[160:161]
	v_mov_b64_e32 v[90:91], v[162:163]
	v_mov_b64_e32 v[84:85], v[164:165]
	v_mov_b64_e32 v[86:87], v[166:167]
	v_add_u32_e32 v156, v155, v128
	v_add_u32_e32 v156, 0x12040, v156
	ds_read2_b32 v[80:81], v156 offset0:0 offset1:1
	ds_read2_b32 v[82:83], v156 offset0:2 offset1:3
	ds_read2_b32 v[6:7], v156 offset0:8 offset1:9
	ds_read2_b32 v[8:9], v156 offset0:10 offset1:11
	ds_read2_b32 v[10:11], v156 offset0:16 offset1:17
	ds_read2_b32 v[12:13], v156 offset0:18 offset1:19
	ds_read2_b32 v[2:3], v156 offset0:24 offset1:25
	ds_read2_b32 v[4:5], v156 offset0:26 offset1:27
	v_cmp_gt_u32_e32 vcc, 64, v15
	v_add_u32_e32 v157, v14, v128
	v_add_u32_e32 v159, 4, v15
	v_cndmask_b32_e32 v157, v227, v157, vcc
	ds_read_b128 v[92:95], v157
	ds_read_b128 v[100:103], v157 offset:32
	ds_read_b128 v[96:99], v157 offset:64
	ds_read_b128 v[104:107], v157 offset:96
	v_cmp_gt_u32_e32 vcc, 64, v159
	v_add_u32_e32 v158, v0, v128
	s_nop 0
	v_cndmask_b32_e32 v158, v227, v158, vcc
	ds_read_b128 v[108:111], v158
	ds_read_b128 v[116:119], v158 offset:32
	ds_read_b128 v[112:115], v158 offset:64
	ds_read_b128 v[120:123], v158 offset:96
	s_setprio 1
	v_mfma_f32_32x32x16_bf16 v[48:63], v[168:171], v[184:187], v[48:63]
	v_mfma_f32_32x32x16_bf16 v[64:79], v[168:171], v[228:231], v[64:79]
	v_mfma_f32_32x32x16_bf16 v[16:31], v[160:163], v[184:187], v[16:31]
	v_mfma_f32_32x32x16_bf16 v[32:47], v[160:163], v[228:231], v[32:47]
	v_mfma_f32_32x32x16_bf16 v[48:63], v[172:175], v[204:207], v[48:63]
	v_mfma_f32_32x32x16_bf16 v[64:79], v[172:175], v[232:235], v[64:79]
	v_mfma_f32_32x32x16_bf16 v[16:31], v[164:167], v[204:207], v[16:31]
	v_mfma_f32_32x32x16_bf16 v[32:47], v[164:167], v[232:235], v[32:47]
	v_mfma_f32_32x32x16_bf16 v[48:63], v[176:179], v[208:211], v[48:63]
	v_mfma_f32_32x32x16_bf16 v[64:79], v[176:179], v[236:239], v[64:79]
	v_mfma_f32_32x32x16_bf16 v[16:31], v[168:171], v[208:211], v[16:31]
	v_mfma_f32_32x32x16_bf16 v[32:47], v[168:171], v[236:239], v[32:47]
	v_mfma_f32_32x32x16_bf16 v[48:63], v[180:183], v[212:215], v[48:63]
	v_mfma_f32_32x32x16_bf16 v[64:79], v[180:183], v[240:243], v[64:79]
	v_mfma_f32_32x32x16_bf16 v[16:31], v[172:175], v[212:215], v[16:31]
	v_mfma_f32_32x32x16_bf16 v[32:47], v[172:175], v[240:243], v[32:47]
	s_setprio 0
	s_branch .Lhy_x
